# wi 11/21 + all GEMM K-loops: snake MFMA order (every MFMA shares accumulator, A fragment or B fragment with its predecessor)
# speedup vs baseline: 1.0184x; 1.0108x over previous
.LBB0_256:
	v_add_u32_e32 v172, s70, v160
	v_add_u32_e32 v188, s71, v160
	ds_read_b128 v[154:157], v172
	ds_read_b128 v[164:167], v172 offset:1024
	ds_read_b128 v[168:171], v172 offset:2048
	ds_read_b128 v[172:175], v172 offset:3072
	ds_read_b128 v[176:179], v188
	ds_read_b128 v[180:183], v188 offset:1024
	ds_read_b128 v[184:187], v188 offset:2048
	ds_read_b128 v[188:191], v188 offset:3072
	s_add_i32 s75, s30, 2
	s_add_u32 s31, s28, 0xfffc0080
	s_addc_u32 s34, s29, -1
	s_cmp_eq_u32 s67, s30
	s_cselect_b32 s30, s26, s17
	s_cselect_b32 s35, s25, s34
	s_cselect_b32 s34, s24, s31
	s_cselect_b32 s31, s27, s19
	v_lshl_add_u64 v[224:225], s[28:29], 0, v[146:147]
	s_add_i32 m0, s58, 0xc000
	ds_read_b128 v[192:195], v163
	ds_read_b128 v[196:199], v163 offset:1024
	ds_read_b128 v[200:203], v163 offset:2048
	ds_read_b128 v[204:207], v163 offset:3072
	ds_read_b128 v[208:211], v163 offset:4096
	ds_read_b128 v[212:215], v163 offset:5120
	ds_read_b128 v[216:219], v163 offset:6144
	ds_read_b128 v[220:223], v163 offset:7168
	global_load_lds_dwordx4 v[224:225], off
	v_lshl_add_u64 v[224:225], s[28:29], 0, v[148:149]
	s_add_i32 m0, s58, 0xe000
	s_nop 0
	global_load_lds_dwordx4 v[224:225], off
	s_waitcnt vmcnt(8)
	s_waitcnt lgkmcnt(0)
	s_barrier
	v_mfma_f32_16x16x32_bf16 v[42:45], v[154:157], v[192:195], v[42:45]
	v_mfma_f32_16x16x32_bf16 v[42:45], v[164:167], v[196:199], v[42:45]
	v_mfma_f32_16x16x32_bf16 v[26:29], v[172:175], v[196:199], v[26:29]
	v_mfma_f32_16x16x32_bf16 v[26:29], v[168:171], v[192:195], v[26:29]
	v_mfma_f32_16x16x32_bf16 v[14:17], v[176:179], v[192:195], v[14:17]
	v_mfma_f32_16x16x32_bf16 v[14:17], v[180:183], v[196:199], v[14:17]
	v_mfma_f32_16x16x32_bf16 v[2:5], v[188:191], v[196:199], v[2:5]
	v_mfma_f32_16x16x32_bf16 v[2:5], v[184:187], v[192:195], v[2:5]
	v_mfma_f32_16x16x32_bf16 v[6:9], v[184:187], v[200:203], v[6:9]
	v_mfma_f32_16x16x32_bf16 v[6:9], v[188:191], v[204:207], v[6:9]
	v_mfma_f32_16x16x32_bf16 v[22:25], v[180:183], v[204:207], v[22:25]
	v_mfma_f32_16x16x32_bf16 v[22:25], v[176:179], v[200:203], v[22:25]
	v_mfma_f32_16x16x32_bf16 v[38:41], v[168:171], v[200:203], v[38:41]
	v_mfma_f32_16x16x32_bf16 v[38:41], v[172:175], v[204:207], v[38:41]
	v_mfma_f32_16x16x32_bf16 v[54:57], v[164:167], v[204:207], v[54:57]
	v_mfma_f32_16x16x32_bf16 v[54:57], v[154:157], v[200:203], v[54:57]
	v_mfma_f32_16x16x32_bf16 v[66:69], v[154:157], v[208:211], v[66:69]
	v_mfma_f32_16x16x32_bf16 v[66:69], v[164:167], v[212:215], v[66:69]
	v_mfma_f32_16x16x32_bf16 v[50:53], v[172:175], v[212:215], v[50:53]
	v_mfma_f32_16x16x32_bf16 v[50:53], v[168:171], v[208:211], v[50:53]
	v_mfma_f32_16x16x32_bf16 v[30:33], v[176:179], v[208:211], v[30:33]
	v_mfma_f32_16x16x32_bf16 v[30:33], v[180:183], v[212:215], v[30:33]
	v_mfma_f32_16x16x32_bf16 v[10:13], v[188:191], v[212:215], v[10:13]
	v_mfma_f32_16x16x32_bf16 v[10:13], v[184:187], v[208:211], v[10:13]
	v_mfma_f32_16x16x32_bf16 v[18:21], v[184:187], v[216:219], v[18:21]
	v_mfma_f32_16x16x32_bf16 v[18:21], v[188:191], v[220:223], v[18:21]
	v_mfma_f32_16x16x32_bf16 v[34:37], v[180:183], v[220:223], v[34:37]
	v_mfma_f32_16x16x32_bf16 v[34:37], v[176:179], v[216:219], v[34:37]
	v_mfma_f32_16x16x32_bf16 v[46:49], v[168:171], v[216:219], v[46:49]
	v_mfma_f32_16x16x32_bf16 v[46:49], v[172:175], v[220:223], v[46:49]
	v_mfma_f32_16x16x32_bf16 v[62:65], v[164:167], v[220:223], v[62:65]
	v_mfma_f32_16x16x32_bf16 v[62:65], v[154:157], v[216:219], v[62:65]
	s_barrier
	s_add_i32 s50, s70, s54
	v_lshl_add_u64 v[224:225], s[30:31], 0, v[134:135]
	s_mov_b32 m0, s50
	ds_read_b128 v[192:195], v163 offset:16384
	ds_read_b128 v[196:199], v163 offset:17408
	ds_read_b128 v[200:203], v163 offset:18432
	ds_read_b128 v[204:207], v163 offset:19456
	ds_read_b128 v[208:211], v163 offset:20480
	ds_read_b128 v[212:215], v163 offset:21504
	ds_read_b128 v[216:219], v163 offset:22528
	ds_read_b128 v[220:223], v163 offset:23552
	global_load_lds_dwordx4 v[224:225], off
	s_add_i32 m0, s50, 0x2000
	s_add_u32 s76, s30, 0x40000
	v_lshl_add_u64 v[226:227], s[30:31], 0, v[130:131]
	s_addc_u32 s77, s31, 0
	s_add_i32 s50, s71, s54
	global_load_lds_dwordx4 v[226:227], off
	v_lshl_add_u64 v[228:229], s[76:77], 0, v[134:135]
	s_mov_b32 m0, s50
	v_lshl_add_u64 v[230:231], s[34:35], 0, v[132:133]
	global_load_lds_dwordx4 v[228:229], off
	v_lshl_add_u64 v[228:229], s[76:77], 0, v[130:131]
	s_add_i32 m0, s50, 0x2000
	s_nop 0
	global_load_lds_dwordx4 v[228:229], off
	v_lshl_add_u64 v[228:229], s[34:35], 0, v[136:137]
	s_mov_b32 m0, s58
	s_nop 0
	global_load_lds_dwordx4 v[228:229], off
	s_mov_b32 m0, s59
	s_nop 0
	global_load_lds_dwordx4 v[230:231], off
	s_waitcnt vmcnt(8)
	s_waitcnt lgkmcnt(0)
	s_barrier
	v_mfma_f32_16x16x32_bf16 v[110:113], v[154:157], v[192:195], v[110:113]
	v_mfma_f32_16x16x32_bf16 v[110:113], v[164:167], v[196:199], v[110:113]
	v_mfma_f32_16x16x32_bf16 v[86:89], v[172:175], v[196:199], v[86:89]
	v_mfma_f32_16x16x32_bf16 v[86:89], v[168:171], v[192:195], v[86:89]
	v_mfma_f32_16x16x32_bf16 v[70:73], v[176:179], v[192:195], v[70:73]
	v_mfma_f32_16x16x32_bf16 v[70:73], v[180:183], v[196:199], v[70:73]
	v_mfma_f32_16x16x32_bf16 v[58:61], v[188:191], v[196:199], v[58:61]
	v_mfma_f32_16x16x32_bf16 v[58:61], v[184:187], v[192:195], v[58:61]
	v_mfma_f32_16x16x32_bf16 v[78:81], v[184:187], v[200:203], v[78:81]
	v_mfma_f32_16x16x32_bf16 v[78:81], v[188:191], v[204:207], v[78:81]
	v_mfma_f32_16x16x32_bf16 v[74:77], v[180:183], v[204:207], v[74:77]
	v_mfma_f32_16x16x32_bf16 v[74:77], v[176:179], v[200:203], v[74:77]
	v_mfma_f32_16x16x32_bf16 v[82:85], v[168:171], v[200:203], v[82:85]
	v_mfma_f32_16x16x32_bf16 v[82:85], v[172:175], v[204:207], v[82:85]
	v_mfma_f32_16x16x32_bf16 v[106:109], v[164:167], v[204:207], v[106:109]
	v_mfma_f32_16x16x32_bf16 v[106:109], v[154:157], v[200:203], v[106:109]
	v_mfma_f32_16x16x32_bf16 v[118:121], v[154:157], v[208:211], v[118:121]
	v_mfma_f32_16x16x32_bf16 v[118:121], v[164:167], v[212:215], v[118:121]
	v_mfma_f32_16x16x32_bf16 v[94:97], v[172:175], v[212:215], v[94:97]
	v_mfma_f32_16x16x32_bf16 v[94:97], v[168:171], v[208:211], v[94:97]
	v_mfma_f32_16x16x32_bf16 v[114:117], v[176:179], v[208:211], v[114:117]
	v_mfma_f32_16x16x32_bf16 v[114:117], v[180:183], v[212:215], v[114:117]
	v_mfma_f32_16x16x32_bf16 v[90:93], v[188:191], v[212:215], v[90:93]
	v_mfma_f32_16x16x32_bf16 v[90:93], v[184:187], v[208:211], v[90:93]
	v_mfma_f32_16x16x32_bf16 v[98:101], v[184:187], v[216:219], v[98:101]
	v_mfma_f32_16x16x32_bf16 v[98:101], v[188:191], v[220:223], v[98:101]
	v_mfma_f32_16x16x32_bf16 v[122:125], v[180:183], v[220:223], v[122:125]
	v_mfma_f32_16x16x32_bf16 v[122:125], v[176:179], v[216:219], v[122:125]
	v_mfma_f32_16x16x32_bf16 v[102:105], v[168:171], v[216:219], v[102:105]
	v_mfma_f32_16x16x32_bf16 v[102:105], v[172:175], v[220:223], v[102:105]
	v_mfma_f32_16x16x32_bf16 v[126:129], v[164:167], v[220:223], v[126:129]
	v_mfma_f32_16x16x32_bf16 v[126:129], v[154:157], v[216:219], v[126:129]
	s_barrier
	s_add_i32 s50, 0, 0x18000
	s_add_i32 s51, 0, 0x1c000
	v_add_u32_e32 v172, s50, v160
	v_add_u32_e32 v188, s51, v160
	ds_read_b128 v[154:157], v172
	ds_read_b128 v[164:167], v172 offset:1024
	ds_read_b128 v[168:171], v172 offset:2048
	ds_read_b128 v[172:175], v172 offset:3072
	ds_read_b128 v[176:179], v188
	ds_read_b128 v[180:183], v188 offset:1024
	ds_read_b128 v[184:187], v188 offset:2048
	ds_read_b128 v[188:191], v188 offset:3072
	s_add_u32 s34, s34, 0x40000
	s_addc_u32 s35, s35, 0
	s_mov_b32 m0, s60
	v_lshl_add_u64 v[232:233], s[34:35], 0, v[136:137]
	ds_read_b128 v[192:195], v163 offset:32768
	ds_read_b128 v[196:199], v163 offset:33792
	ds_read_b128 v[200:203], v163 offset:34816
	ds_read_b128 v[204:207], v163 offset:35840
	ds_read_b128 v[208:211], v163 offset:36864
	ds_read_b128 v[212:215], v163 offset:37888
	ds_read_b128 v[216:219], v163 offset:38912
	ds_read_b128 v[220:223], v163 offset:39936
	global_load_lds_dwordx4 v[232:233], off
	v_lshl_add_u64 v[232:233], s[34:35], 0, v[132:133]
	s_mov_b32 m0, s61
	s_nop 0
	global_load_lds_dwordx4 v[232:233], off
	s_waitcnt vmcnt(8)
	s_waitcnt lgkmcnt(0)
	s_barrier
	v_mfma_f32_16x16x32_bf16 v[42:45], v[154:157], v[192:195], v[42:45]
	v_mfma_f32_16x16x32_bf16 v[42:45], v[164:167], v[196:199], v[42:45]
	v_mfma_f32_16x16x32_bf16 v[26:29], v[172:175], v[196:199], v[26:29]
	v_mfma_f32_16x16x32_bf16 v[26:29], v[168:171], v[192:195], v[26:29]
	v_mfma_f32_16x16x32_bf16 v[14:17], v[176:179], v[192:195], v[14:17]
	v_mfma_f32_16x16x32_bf16 v[14:17], v[180:183], v[196:199], v[14:17]
	v_mfma_f32_16x16x32_bf16 v[2:5], v[188:191], v[196:199], v[2:5]
	v_mfma_f32_16x16x32_bf16 v[2:5], v[184:187], v[192:195], v[2:5]
	v_mfma_f32_16x16x32_bf16 v[6:9], v[184:187], v[200:203], v[6:9]
	v_mfma_f32_16x16x32_bf16 v[6:9], v[188:191], v[204:207], v[6:9]
	v_mfma_f32_16x16x32_bf16 v[22:25], v[180:183], v[204:207], v[22:25]
	v_mfma_f32_16x16x32_bf16 v[22:25], v[176:179], v[200:203], v[22:25]
	v_mfma_f32_16x16x32_bf16 v[38:41], v[168:171], v[200:203], v[38:41]
	v_mfma_f32_16x16x32_bf16 v[38:41], v[172:175], v[204:207], v[38:41]
	v_mfma_f32_16x16x32_bf16 v[54:57], v[164:167], v[204:207], v[54:57]
	v_mfma_f32_16x16x32_bf16 v[54:57], v[154:157], v[200:203], v[54:57]
	v_mfma_f32_16x16x32_bf16 v[66:69], v[154:157], v[208:211], v[66:69]
	v_mfma_f32_16x16x32_bf16 v[66:69], v[164:167], v[212:215], v[66:69]
	v_mfma_f32_16x16x32_bf16 v[50:53], v[172:175], v[212:215], v[50:53]
	v_mfma_f32_16x16x32_bf16 v[50:53], v[168:171], v[208:211], v[50:53]
	v_mfma_f32_16x16x32_bf16 v[30:33], v[176:179], v[208:211], v[30:33]
	v_mfma_f32_16x16x32_bf16 v[30:33], v[180:183], v[212:215], v[30:33]
	v_mfma_f32_16x16x32_bf16 v[10:13], v[188:191], v[212:215], v[10:13]
	v_mfma_f32_16x16x32_bf16 v[10:13], v[184:187], v[208:211], v[10:13]
	v_mfma_f32_16x16x32_bf16 v[18:21], v[184:187], v[216:219], v[18:21]
	v_mfma_f32_16x16x32_bf16 v[18:21], v[188:191], v[220:223], v[18:21]
	v_mfma_f32_16x16x32_bf16 v[34:37], v[180:183], v[220:223], v[34:37]
	v_mfma_f32_16x16x32_bf16 v[34:37], v[176:179], v[216:219], v[34:37]
	v_mfma_f32_16x16x32_bf16 v[46:49], v[168:171], v[216:219], v[46:49]
	v_mfma_f32_16x16x32_bf16 v[46:49], v[172:175], v[220:223], v[46:49]
	v_mfma_f32_16x16x32_bf16 v[62:65], v[164:167], v[220:223], v[62:65]
	v_mfma_f32_16x16x32_bf16 v[62:65], v[154:157], v[216:219], v[62:65]
	s_barrier
	s_add_i32 s34, s50, s54
	v_lshl_add_u64 v[224:225], v[224:225], 0, s[10:11]
	s_mov_b32 m0, s34
	ds_read_b128 v[192:195], v163 offset:49152
	ds_read_b128 v[196:199], v163 offset:50176
	ds_read_b128 v[200:203], v163 offset:51200
	ds_read_b128 v[204:207], v163 offset:52224
	ds_read_b128 v[208:211], v163 offset:53248
	ds_read_b128 v[212:215], v163 offset:54272
	ds_read_b128 v[216:219], v163 offset:55296
	ds_read_b128 v[220:223], v163 offset:56320
	global_load_lds_dwordx4 v[224:225], off
	s_add_i32 m0, s34, 0x2000
	s_add_u32 s30, s30, 0x40080
	v_lshl_add_u64 v[224:225], v[226:227], 0, s[10:11]
	s_addc_u32 s31, s31, 0
	s_add_i32 s34, s51, s54
	global_load_lds_dwordx4 v[224:225], off
	v_lshl_add_u64 v[224:225], s[30:31], 0, v[134:135]
	s_mov_b32 m0, s34
	s_nop 0
	global_load_lds_dwordx4 v[224:225], off
	v_lshl_add_u64 v[224:225], s[30:31], 0, v[130:131]
	s_add_i32 m0, s34, 0x2000
	s_nop 0
	global_load_lds_dwordx4 v[224:225], off
	v_lshl_add_u64 v[224:225], v[228:229], 0, s[10:11]
	s_mov_b32 m0, s65
	s_nop 0
	global_load_lds_dwordx4 v[224:225], off
	v_lshl_add_u64 v[224:225], v[230:231], 0, s[10:11]
	s_mov_b32 m0, s66
	s_nop 0
	global_load_lds_dwordx4 v[224:225], off
	s_waitcnt vmcnt(8)
	s_waitcnt lgkmcnt(0)
	s_barrier
	v_mfma_f32_16x16x32_bf16 v[110:113], v[154:157], v[192:195], v[110:113]
	v_mfma_f32_16x16x32_bf16 v[110:113], v[164:167], v[196:199], v[110:113]
	v_mfma_f32_16x16x32_bf16 v[86:89], v[172:175], v[196:199], v[86:89]
	v_mfma_f32_16x16x32_bf16 v[86:89], v[168:171], v[192:195], v[86:89]
	v_mfma_f32_16x16x32_bf16 v[70:73], v[176:179], v[192:195], v[70:73]
	v_mfma_f32_16x16x32_bf16 v[70:73], v[180:183], v[196:199], v[70:73]
	v_mfma_f32_16x16x32_bf16 v[58:61], v[188:191], v[196:199], v[58:61]
	v_mfma_f32_16x16x32_bf16 v[58:61], v[184:187], v[192:195], v[58:61]
	v_mfma_f32_16x16x32_bf16 v[78:81], v[184:187], v[200:203], v[78:81]
	v_mfma_f32_16x16x32_bf16 v[78:81], v[188:191], v[204:207], v[78:81]
	v_mfma_f32_16x16x32_bf16 v[74:77], v[180:183], v[204:207], v[74:77]
	v_mfma_f32_16x16x32_bf16 v[74:77], v[176:179], v[200:203], v[74:77]
	v_mfma_f32_16x16x32_bf16 v[82:85], v[168:171], v[200:203], v[82:85]
	v_mfma_f32_16x16x32_bf16 v[82:85], v[172:175], v[204:207], v[82:85]
	v_mfma_f32_16x16x32_bf16 v[106:109], v[164:167], v[204:207], v[106:109]
	v_mfma_f32_16x16x32_bf16 v[106:109], v[154:157], v[200:203], v[106:109]
	v_mfma_f32_16x16x32_bf16 v[118:121], v[154:157], v[208:211], v[118:121]
	v_mfma_f32_16x16x32_bf16 v[118:121], v[164:167], v[212:215], v[118:121]
	v_mfma_f32_16x16x32_bf16 v[94:97], v[172:175], v[212:215], v[94:97]
	v_mfma_f32_16x16x32_bf16 v[94:97], v[168:171], v[208:211], v[94:97]
	v_mfma_f32_16x16x32_bf16 v[114:117], v[176:179], v[208:211], v[114:117]
	v_mfma_f32_16x16x32_bf16 v[114:117], v[180:183], v[212:215], v[114:117]
	v_mfma_f32_16x16x32_bf16 v[90:93], v[188:191], v[212:215], v[90:93]
	v_mfma_f32_16x16x32_bf16 v[90:93], v[184:187], v[208:211], v[90:93]
	v_mfma_f32_16x16x32_bf16 v[98:101], v[184:187], v[216:219], v[98:101]
	v_mfma_f32_16x16x32_bf16 v[98:101], v[188:191], v[220:223], v[98:101]
	v_mfma_f32_16x16x32_bf16 v[122:125], v[180:183], v[220:223], v[122:125]
	v_mfma_f32_16x16x32_bf16 v[122:125], v[176:179], v[216:219], v[122:125]
	v_mfma_f32_16x16x32_bf16 v[102:105], v[168:171], v[216:219], v[102:105]
	v_mfma_f32_16x16x32_bf16 v[102:105], v[172:175], v[220:223], v[102:105]
	v_mfma_f32_16x16x32_bf16 v[126:129], v[164:167], v[220:223], v[126:129]
	v_mfma_f32_16x16x32_bf16 v[126:129], v[154:157], v[216:219], v[126:129]
	s_barrier
	s_add_u32 s28, s28, 0x100
	s_addc_u32 s29, s29, 0
	s_add_u32 s17, s17, 0x100
	s_addc_u32 s19, s19, 0
	s_cmp_ge_i32 s75, s62
	s_mov_b32 s30, s75
	s_cbranch_scc0 .LBB0_256

.LBB0_351:
	v_add_u32_e32 v81, s62, v78
	s_waitcnt lgkmcnt(0)
	ds_read_b128 v[82:85], v81
	ds_read_b128 v[86:89], v81 offset:1024
	ds_read_b128 v[90:93], v81 offset:2048
	ds_read_b128 v[94:97], v81 offset:3072
	s_add_i32 s72, s24, 2
	s_add_u32 s22, s20, 0x100
	s_addc_u32 s23, s21, 0
	s_cmp_eq_u32 s61, s24
	s_cselect_b32 s24, s16, s70
	s_cselect_b32 s27, s15, s23
	s_cselect_b32 s26, s14, s22
	s_cselect_b32 s25, s17, s71
	s_mov_b32 m0, s63
	v_lshl_add_u64 v[130:131], s[20:21], 0, v[74:75]
	ds_read_b128 v[98:101], v79
	ds_read_b128 v[102:105], v79 offset:1024
	ds_read_b128 v[106:109], v79 offset:2048
	ds_read_b128 v[110:113], v79 offset:3072
	ds_read_b128 v[114:117], v79 offset:4096
	ds_read_b128 v[118:121], v79 offset:5120
	ds_read_b128 v[122:125], v79 offset:6144
	ds_read_b128 v[126:129], v79 offset:7168
	global_load_lds_dwordx4 v[130:131], off
	v_lshl_add_u64 v[130:131], s[20:21], 0, v[76:77]
	s_mov_b32 m0, s64
	s_nop 0
	global_load_lds_dwordx4 v[130:131], off
	s_waitcnt vmcnt(8)
	s_waitcnt lgkmcnt(0)
	s_barrier
	v_mfma_f32_16x16x32_bf16 v[62:65], v[82:85], v[98:101], v[62:65]
	v_mfma_f32_16x16x32_bf16 v[62:65], v[86:89], v[102:105], v[62:65]
	v_mfma_f32_16x16x32_bf16 v[58:61], v[94:97], v[102:105], v[58:61]
	v_mfma_f32_16x16x32_bf16 v[58:61], v[90:93], v[98:101], v[58:61]
	v_mfma_f32_16x16x32_bf16 v[50:53], v[90:93], v[106:109], v[50:53]
	v_mfma_f32_16x16x32_bf16 v[50:53], v[94:97], v[110:113], v[50:53]
	v_mfma_f32_16x16x32_bf16 v[54:57], v[86:89], v[110:113], v[54:57]
	v_mfma_f32_16x16x32_bf16 v[54:57], v[82:85], v[106:109], v[54:57]
	v_mfma_f32_16x16x32_bf16 v[46:49], v[82:85], v[114:117], v[46:49]
	v_mfma_f32_16x16x32_bf16 v[46:49], v[86:89], v[118:121], v[46:49]
	v_mfma_f32_16x16x32_bf16 v[42:45], v[94:97], v[118:121], v[42:45]
	v_mfma_f32_16x16x32_bf16 v[42:45], v[90:93], v[114:117], v[42:45]
	v_mfma_f32_16x16x32_bf16 v[26:29], v[90:93], v[122:125], v[26:29]
	v_mfma_f32_16x16x32_bf16 v[26:29], v[94:97], v[126:129], v[26:29]
	v_mfma_f32_16x16x32_bf16 v[34:37], v[86:89], v[126:129], v[34:37]
	v_mfma_f32_16x16x32_bf16 v[34:37], v[82:85], v[122:125], v[34:37]
	s_barrier
	s_mov_b32 m0, s65
	v_lshl_add_u64 v[130:131], s[24:25], 0, v[70:71]
	s_add_u32 s20, s24, 0x10000
	ds_read_b128 v[98:101], v79 offset:16384
	ds_read_b128 v[102:105], v79 offset:17408
	ds_read_b128 v[106:109], v79 offset:18432
	ds_read_b128 v[110:113], v79 offset:19456
	ds_read_b128 v[114:117], v79 offset:20480
	ds_read_b128 v[118:121], v79 offset:21504
	ds_read_b128 v[122:125], v79 offset:22528
	ds_read_b128 v[126:129], v79 offset:23552
	global_load_lds_dwordx4 v[130:131], off
	v_lshl_add_u64 v[132:133], s[24:25], 0, v[66:67]
	s_mov_b32 m0, s66
	s_addc_u32 s21, s25, 0
	global_load_lds_dwordx4 v[132:133], off
	v_lshl_add_u64 v[134:135], s[20:21], 0, v[70:71]
	s_mov_b32 m0, s34
	v_lshl_add_u64 v[136:137], s[26:27], 0, v[68:69]
	global_load_lds_dwordx4 v[134:135], off
	v_lshl_add_u64 v[134:135], s[20:21], 0, v[66:67]
	s_mov_b32 m0, s35
	s_nop 0
	global_load_lds_dwordx4 v[134:135], off
	v_lshl_add_u64 v[134:135], s[26:27], 0, v[72:73]
	s_mov_b32 m0, s31
	s_nop 0
	global_load_lds_dwordx4 v[134:135], off
	s_mov_b32 m0, s52
	s_nop 0
	global_load_lds_dwordx4 v[136:137], off
	s_waitcnt vmcnt(8)
	s_waitcnt lgkmcnt(0)
	s_barrier
	v_mfma_f32_16x16x32_bf16 v[38:41], v[82:85], v[98:101], v[38:41]
	v_mfma_f32_16x16x32_bf16 v[38:41], v[86:89], v[102:105], v[38:41]
	v_mfma_f32_16x16x32_bf16 v[30:33], v[94:97], v[102:105], v[30:33]
	v_mfma_f32_16x16x32_bf16 v[30:33], v[90:93], v[98:101], v[30:33]
	v_mfma_f32_16x16x32_bf16 v[18:21], v[90:93], v[106:109], v[18:21]
	v_mfma_f32_16x16x32_bf16 v[18:21], v[94:97], v[110:113], v[18:21]
	v_mfma_f32_16x16x32_bf16 v[22:25], v[86:89], v[110:113], v[22:25]
	v_mfma_f32_16x16x32_bf16 v[22:25], v[82:85], v[106:109], v[22:25]
	v_mfma_f32_16x16x32_bf16 v[14:17], v[82:85], v[114:117], v[14:17]
	v_mfma_f32_16x16x32_bf16 v[14:17], v[86:89], v[118:121], v[14:17]
	v_mfma_f32_16x16x32_bf16 v[10:13], v[94:97], v[118:121], v[10:13]
	v_mfma_f32_16x16x32_bf16 v[10:13], v[90:93], v[114:117], v[10:13]
	v_mfma_f32_16x16x32_bf16 v[2:5], v[90:93], v[122:125], v[2:5]
	v_mfma_f32_16x16x32_bf16 v[2:5], v[94:97], v[126:129], v[2:5]
	v_mfma_f32_16x16x32_bf16 v[6:9], v[86:89], v[126:129], v[6:9]
	v_mfma_f32_16x16x32_bf16 v[6:9], v[82:85], v[122:125], v[6:9]
	s_barrier
	v_add_u32_e32 v81, s67, v78
	ds_read_b128 v[82:85], v81
	ds_read_b128 v[86:89], v81 offset:1024
	ds_read_b128 v[90:93], v81 offset:2048
	ds_read_b128 v[94:97], v81 offset:3072
	s_add_u32 s20, s26, 0x18000
	s_addc_u32 s21, s27, 0
	s_mov_b32 m0, s53
	v_lshl_add_u64 v[138:139], s[20:21], 0, v[72:73]
	ds_read_b128 v[98:101], v79 offset:32768
	ds_read_b128 v[102:105], v79 offset:33792
	ds_read_b128 v[106:109], v79 offset:34816
	ds_read_b128 v[110:113], v79 offset:35840
	ds_read_b128 v[114:117], v79 offset:36864
	ds_read_b128 v[118:121], v79 offset:37888
	ds_read_b128 v[122:125], v79 offset:38912
	ds_read_b128 v[126:129], v79 offset:39936
	global_load_lds_dwordx4 v[138:139], off
	v_lshl_add_u64 v[138:139], s[20:21], 0, v[68:69]
	s_mov_b32 m0, s54
	s_nop 0
	global_load_lds_dwordx4 v[138:139], off
	s_waitcnt vmcnt(8)
	s_waitcnt lgkmcnt(0)
	s_barrier
	v_mfma_f32_16x16x32_bf16 v[62:65], v[82:85], v[98:101], v[62:65]
	v_mfma_f32_16x16x32_bf16 v[62:65], v[86:89], v[102:105], v[62:65]
	v_mfma_f32_16x16x32_bf16 v[58:61], v[94:97], v[102:105], v[58:61]
	v_mfma_f32_16x16x32_bf16 v[58:61], v[90:93], v[98:101], v[58:61]
	v_mfma_f32_16x16x32_bf16 v[50:53], v[90:93], v[106:109], v[50:53]
	v_mfma_f32_16x16x32_bf16 v[50:53], v[94:97], v[110:113], v[50:53]
	v_mfma_f32_16x16x32_bf16 v[54:57], v[86:89], v[110:113], v[54:57]
	v_mfma_f32_16x16x32_bf16 v[54:57], v[82:85], v[106:109], v[54:57]
	v_mfma_f32_16x16x32_bf16 v[46:49], v[82:85], v[114:117], v[46:49]
	v_mfma_f32_16x16x32_bf16 v[46:49], v[86:89], v[118:121], v[46:49]
	v_mfma_f32_16x16x32_bf16 v[42:45], v[94:97], v[118:121], v[42:45]
	v_mfma_f32_16x16x32_bf16 v[42:45], v[90:93], v[114:117], v[42:45]
	v_mfma_f32_16x16x32_bf16 v[26:29], v[90:93], v[122:125], v[26:29]
	v_mfma_f32_16x16x32_bf16 v[26:29], v[94:97], v[126:129], v[26:29]
	v_mfma_f32_16x16x32_bf16 v[34:37], v[86:89], v[126:129], v[34:37]
	v_mfma_f32_16x16x32_bf16 v[34:37], v[82:85], v[122:125], v[34:37]
	s_barrier
	s_mov_b32 m0, s68
	v_lshl_add_u64 v[130:131], v[130:131], 0, s[6:7]
	s_add_u32 s20, s24, 0x10080
	ds_read_b128 v[98:101], v79 offset:49152
	ds_read_b128 v[102:105], v79 offset:50176
	ds_read_b128 v[106:109], v79 offset:51200
	ds_read_b128 v[110:113], v79 offset:52224
	ds_read_b128 v[114:117], v79 offset:53248
	ds_read_b128 v[118:121], v79 offset:54272
	ds_read_b128 v[122:125], v79 offset:55296
	ds_read_b128 v[126:129], v79 offset:56320
	global_load_lds_dwordx4 v[130:131], off
	v_lshl_add_u64 v[130:131], v[132:133], 0, s[6:7]
	s_mov_b32 m0, s69
	s_addc_u32 s21, s25, 0
	global_load_lds_dwordx4 v[130:131], off
	v_lshl_add_u64 v[130:131], s[20:21], 0, v[70:71]
	s_mov_b32 m0, s59
	s_nop 0
	global_load_lds_dwordx4 v[130:131], off
	v_lshl_add_u64 v[130:131], s[20:21], 0, v[66:67]
	s_mov_b32 m0, s60
	s_nop 0
	global_load_lds_dwordx4 v[130:131], off
	v_lshl_add_u64 v[130:131], v[134:135], 0, s[6:7]
	s_mov_b32 m0, s57
	s_nop 0
	global_load_lds_dwordx4 v[130:131], off
	v_lshl_add_u64 v[130:131], v[136:137], 0, s[6:7]
	s_mov_b32 m0, s58
	s_nop 0
	global_load_lds_dwordx4 v[130:131], off
	s_waitcnt vmcnt(8)
	s_waitcnt lgkmcnt(0)
	s_barrier
	v_mfma_f32_16x16x32_bf16 v[38:41], v[82:85], v[98:101], v[38:41]
	v_mfma_f32_16x16x32_bf16 v[38:41], v[86:89], v[102:105], v[38:41]
	v_mfma_f32_16x16x32_bf16 v[30:33], v[94:97], v[102:105], v[30:33]
	v_mfma_f32_16x16x32_bf16 v[30:33], v[90:93], v[98:101], v[30:33]
	v_mfma_f32_16x16x32_bf16 v[18:21], v[90:93], v[106:109], v[18:21]
	v_mfma_f32_16x16x32_bf16 v[18:21], v[94:97], v[110:113], v[18:21]
	v_mfma_f32_16x16x32_bf16 v[22:25], v[86:89], v[110:113], v[22:25]
	v_mfma_f32_16x16x32_bf16 v[22:25], v[82:85], v[106:109], v[22:25]
	v_mfma_f32_16x16x32_bf16 v[14:17], v[82:85], v[114:117], v[14:17]
	v_mfma_f32_16x16x32_bf16 v[14:17], v[86:89], v[118:121], v[14:17]
	v_mfma_f32_16x16x32_bf16 v[10:13], v[94:97], v[118:121], v[10:13]
	v_mfma_f32_16x16x32_bf16 v[10:13], v[90:93], v[114:117], v[10:13]
	v_mfma_f32_16x16x32_bf16 v[2:5], v[90:93], v[122:125], v[2:5]
	v_mfma_f32_16x16x32_bf16 v[2:5], v[94:97], v[126:129], v[2:5]
	v_mfma_f32_16x16x32_bf16 v[6:9], v[86:89], v[126:129], v[6:9]
	v_mfma_f32_16x16x32_bf16 v[6:9], v[82:85], v[122:125], v[6:9]
	s_barrier
	s_add_u32 s70, s70, 0x100
	s_addc_u32 s71, s71, 0
	s_cmp_ge_i32 s72, s56
	s_mov_b64 s[20:21], s[22:23]
	s_mov_b32 s24, s72
	s_cbranch_scc0 .LBB0_351

.LBB0_468:
	v_add_u32_e32 v144, s62, v1
	ds_read_b128 v[150:153], v144
	ds_read_b128 v[154:157], v144 offset:1024
	ds_read_b128 v[158:161], v144 offset:2048
	ds_read_b128 v[162:165], v144 offset:3072
	v_add_u32_e32 v144, s63, v1
	ds_read_b128 v[166:169], v144
	ds_read_b128 v[170:173], v144 offset:1024
	ds_read_b128 v[174:177], v144 offset:2048
	ds_read_b128 v[178:181], v144 offset:3072
	s_add_i32 s77, s26, 2
	s_add_u32 s24, s22, 0x100
	s_addc_u32 s25, s23, 0
	s_cmp_eq_u32 s61, s26
	s_cselect_b32 s26, s16, s75
	s_cselect_b32 s29, s15, s25
	s_cselect_b32 s28, s14, s24
	s_cselect_b32 s27, s17, s76
	s_mov_b32 m0, s64
	v_lshl_add_u64 v[144:145], s[22:23], 0, v[140:141]
	ds_read_b128 v[182:185], v149
	ds_read_b128 v[186:189], v149 offset:1024
	ds_read_b128 v[190:193], v149 offset:2048
	ds_read_b128 v[194:197], v149 offset:3072
	ds_read_b128 v[198:201], v149 offset:4096
	ds_read_b128 v[202:205], v149 offset:5120
	ds_read_b128 v[206:209], v149 offset:6144
	ds_read_b128 v[210:213], v149 offset:7168
	global_load_lds_dwordx4 v[144:145], off
	v_lshl_add_u64 v[144:145], s[22:23], 0, v[142:143]
	s_mov_b32 m0, s65
	s_nop 0
	global_load_lds_dwordx4 v[144:145], off
	s_waitcnt vmcnt(8)
	s_waitcnt lgkmcnt(0)
	s_barrier
	v_mfma_f32_16x16x32_bf16 v[126:129], v[150:153], v[182:185], v[126:129]
	v_mfma_f32_16x16x32_bf16 v[126:129], v[154:157], v[186:189], v[126:129]
	v_mfma_f32_16x16x32_bf16 v[122:125], v[162:165], v[186:189], v[122:125]
	v_mfma_f32_16x16x32_bf16 v[122:125], v[158:161], v[182:185], v[122:125]
	v_mfma_f32_16x16x32_bf16 v[118:121], v[166:169], v[182:185], v[118:121]
	v_mfma_f32_16x16x32_bf16 v[118:121], v[170:173], v[186:189], v[118:121]
	v_mfma_f32_16x16x32_bf16 v[114:117], v[178:181], v[186:189], v[114:117]
	v_mfma_f32_16x16x32_bf16 v[114:117], v[174:177], v[182:185], v[114:117]
	v_mfma_f32_16x16x32_bf16 v[98:101], v[174:177], v[190:193], v[98:101]
	v_mfma_f32_16x16x32_bf16 v[98:101], v[178:181], v[194:197], v[98:101]
	v_mfma_f32_16x16x32_bf16 v[102:105], v[170:173], v[194:197], v[102:105]
	v_mfma_f32_16x16x32_bf16 v[102:105], v[166:169], v[190:193], v[102:105]
	v_mfma_f32_16x16x32_bf16 v[106:109], v[158:161], v[190:193], v[106:109]
	v_mfma_f32_16x16x32_bf16 v[106:109], v[162:165], v[194:197], v[106:109]
	v_mfma_f32_16x16x32_bf16 v[110:113], v[154:157], v[194:197], v[110:113]
	v_mfma_f32_16x16x32_bf16 v[110:113], v[150:153], v[190:193], v[110:113]
	v_mfma_f32_16x16x32_bf16 v[94:97], v[150:153], v[198:201], v[94:97]
	v_mfma_f32_16x16x32_bf16 v[94:97], v[154:157], v[202:205], v[94:97]
	v_mfma_f32_16x16x32_bf16 v[90:93], v[162:165], v[202:205], v[90:93]
	v_mfma_f32_16x16x32_bf16 v[90:93], v[158:161], v[198:201], v[90:93]
	v_mfma_f32_16x16x32_bf16 v[86:89], v[166:169], v[198:201], v[86:89]
	v_mfma_f32_16x16x32_bf16 v[86:89], v[170:173], v[202:205], v[86:89]
	v_mfma_f32_16x16x32_bf16 v[82:85], v[178:181], v[202:205], v[82:85]
	v_mfma_f32_16x16x32_bf16 v[82:85], v[174:177], v[198:201], v[82:85]
	v_mfma_f32_16x16x32_bf16 v[66:69], v[174:177], v[206:209], v[66:69]
	v_mfma_f32_16x16x32_bf16 v[66:69], v[178:181], v[210:213], v[66:69]
	v_mfma_f32_16x16x32_bf16 v[70:73], v[170:173], v[210:213], v[70:73]
	v_mfma_f32_16x16x32_bf16 v[70:73], v[166:169], v[206:209], v[70:73]
	v_mfma_f32_16x16x32_bf16 v[74:77], v[158:161], v[206:209], v[74:77]
	v_mfma_f32_16x16x32_bf16 v[74:77], v[162:165], v[210:213], v[74:77]
	v_mfma_f32_16x16x32_bf16 v[78:81], v[154:157], v[210:213], v[78:81]
	v_mfma_f32_16x16x32_bf16 v[78:81], v[150:153], v[206:209], v[78:81]
	s_barrier
	s_mov_b32 m0, s66
	v_lshl_add_u64 v[144:145], s[26:27], 0, v[134:135]
	s_add_u32 s22, s26, 0x18000
	ds_read_b128 v[182:185], v149 offset:16384
	ds_read_b128 v[186:189], v149 offset:17408
	ds_read_b128 v[190:193], v149 offset:18432
	ds_read_b128 v[194:197], v149 offset:19456
	ds_read_b128 v[198:201], v149 offset:20480
	ds_read_b128 v[202:205], v149 offset:21504
	ds_read_b128 v[206:209], v149 offset:22528
	ds_read_b128 v[210:213], v149 offset:23552
	global_load_lds_dwordx4 v[144:145], off
	v_lshl_add_u64 v[214:215], s[26:27], 0, v[130:131]
	s_mov_b32 m0, s67
	s_addc_u32 s23, s27, 0
	global_load_lds_dwordx4 v[214:215], off
	v_lshl_add_u64 v[216:217], s[22:23], 0, v[134:135]
	s_mov_b32 m0, s68
	v_lshl_add_u64 v[218:219], s[28:29], 0, v[132:133]
	global_load_lds_dwordx4 v[216:217], off
	v_lshl_add_u64 v[216:217], s[22:23], 0, v[130:131]
	s_mov_b32 m0, s69
	s_nop 0
	global_load_lds_dwordx4 v[216:217], off
	v_lshl_add_u64 v[216:217], s[28:29], 0, v[136:137]
	s_mov_b32 m0, s34
	s_nop 0
	global_load_lds_dwordx4 v[216:217], off
	s_mov_b32 m0, s35
	s_nop 0
	global_load_lds_dwordx4 v[218:219], off
	s_waitcnt vmcnt(8)
	s_waitcnt lgkmcnt(0)
	s_barrier
	v_mfma_f32_16x16x32_bf16 v[62:65], v[150:153], v[182:185], v[62:65]
	v_mfma_f32_16x16x32_bf16 v[62:65], v[154:157], v[186:189], v[62:65]
	v_mfma_f32_16x16x32_bf16 v[58:61], v[162:165], v[186:189], v[58:61]
	v_mfma_f32_16x16x32_bf16 v[58:61], v[158:161], v[182:185], v[58:61]
	v_mfma_f32_16x16x32_bf16 v[54:57], v[166:169], v[182:185], v[54:57]
	v_mfma_f32_16x16x32_bf16 v[54:57], v[170:173], v[186:189], v[54:57]
	v_mfma_f32_16x16x32_bf16 v[50:53], v[178:181], v[186:189], v[50:53]
	v_mfma_f32_16x16x32_bf16 v[50:53], v[174:177], v[182:185], v[50:53]
	v_mfma_f32_16x16x32_bf16 v[34:37], v[174:177], v[190:193], v[34:37]
	v_mfma_f32_16x16x32_bf16 v[34:37], v[178:181], v[194:197], v[34:37]
	v_mfma_f32_16x16x32_bf16 v[38:41], v[170:173], v[194:197], v[38:41]
	v_mfma_f32_16x16x32_bf16 v[38:41], v[166:169], v[190:193], v[38:41]
	v_mfma_f32_16x16x32_bf16 v[42:45], v[158:161], v[190:193], v[42:45]
	v_mfma_f32_16x16x32_bf16 v[42:45], v[162:165], v[194:197], v[42:45]
	v_mfma_f32_16x16x32_bf16 v[46:49], v[154:157], v[194:197], v[46:49]
	v_mfma_f32_16x16x32_bf16 v[46:49], v[150:153], v[190:193], v[46:49]
	v_mfma_f32_16x16x32_bf16 v[30:33], v[150:153], v[198:201], v[30:33]
	v_mfma_f32_16x16x32_bf16 v[30:33], v[154:157], v[202:205], v[30:33]
	v_mfma_f32_16x16x32_bf16 v[26:29], v[162:165], v[202:205], v[26:29]
	v_mfma_f32_16x16x32_bf16 v[26:29], v[158:161], v[198:201], v[26:29]
	v_mfma_f32_16x16x32_bf16 v[22:25], v[166:169], v[198:201], v[22:25]
	v_mfma_f32_16x16x32_bf16 v[22:25], v[170:173], v[202:205], v[22:25]
	v_mfma_f32_16x16x32_bf16 v[18:21], v[178:181], v[202:205], v[18:21]
	v_mfma_f32_16x16x32_bf16 v[18:21], v[174:177], v[198:201], v[18:21]
	v_mfma_f32_16x16x32_bf16 v[2:5], v[174:177], v[206:209], v[2:5]
	v_mfma_f32_16x16x32_bf16 v[2:5], v[178:181], v[210:213], v[2:5]
	v_mfma_f32_16x16x32_bf16 v[6:9], v[170:173], v[210:213], v[6:9]
	v_mfma_f32_16x16x32_bf16 v[6:9], v[166:169], v[206:209], v[6:9]
	v_mfma_f32_16x16x32_bf16 v[10:13], v[158:161], v[206:209], v[10:13]
	v_mfma_f32_16x16x32_bf16 v[10:13], v[162:165], v[210:213], v[10:13]
	v_mfma_f32_16x16x32_bf16 v[14:17], v[154:157], v[210:213], v[14:17]
	v_mfma_f32_16x16x32_bf16 v[14:17], v[150:153], v[206:209], v[14:17]
	s_barrier
	v_add_u32_e32 v162, s70, v1
	v_add_u32_e32 v178, s71, v1
	ds_read_b128 v[150:153], v162
	ds_read_b128 v[154:157], v162 offset:1024
	ds_read_b128 v[158:161], v162 offset:2048
	ds_read_b128 v[162:165], v162 offset:3072
	ds_read_b128 v[166:169], v178
	ds_read_b128 v[170:173], v178 offset:1024
	ds_read_b128 v[174:177], v178 offset:2048
	ds_read_b128 v[178:181], v178 offset:3072
	s_add_u32 s22, s28, 0x18000
	s_addc_u32 s23, s29, 0
	s_mov_b32 m0, s52
	v_lshl_add_u64 v[220:221], s[22:23], 0, v[136:137]
	ds_read_b128 v[182:185], v149 offset:32768
	ds_read_b128 v[186:189], v149 offset:33792
	ds_read_b128 v[190:193], v149 offset:34816
	ds_read_b128 v[194:197], v149 offset:35840
	ds_read_b128 v[198:201], v149 offset:36864
	ds_read_b128 v[202:205], v149 offset:37888
	ds_read_b128 v[206:209], v149 offset:38912
	ds_read_b128 v[210:213], v149 offset:39936
	global_load_lds_dwordx4 v[220:221], off
	v_lshl_add_u64 v[220:221], s[22:23], 0, v[132:133]
	s_mov_b32 m0, s53
	s_nop 0
	global_load_lds_dwordx4 v[220:221], off
	s_waitcnt vmcnt(8)
	s_waitcnt lgkmcnt(0)
	s_barrier
	v_mfma_f32_16x16x32_bf16 v[126:129], v[150:153], v[182:185], v[126:129]
	v_mfma_f32_16x16x32_bf16 v[126:129], v[154:157], v[186:189], v[126:129]
	v_mfma_f32_16x16x32_bf16 v[122:125], v[162:165], v[186:189], v[122:125]
	v_mfma_f32_16x16x32_bf16 v[122:125], v[158:161], v[182:185], v[122:125]
	v_mfma_f32_16x16x32_bf16 v[118:121], v[166:169], v[182:185], v[118:121]
	v_mfma_f32_16x16x32_bf16 v[118:121], v[170:173], v[186:189], v[118:121]
	v_mfma_f32_16x16x32_bf16 v[114:117], v[178:181], v[186:189], v[114:117]
	v_mfma_f32_16x16x32_bf16 v[114:117], v[174:177], v[182:185], v[114:117]
	v_mfma_f32_16x16x32_bf16 v[98:101], v[174:177], v[190:193], v[98:101]
	v_mfma_f32_16x16x32_bf16 v[98:101], v[178:181], v[194:197], v[98:101]
	v_mfma_f32_16x16x32_bf16 v[102:105], v[170:173], v[194:197], v[102:105]
	v_mfma_f32_16x16x32_bf16 v[102:105], v[166:169], v[190:193], v[102:105]
	v_mfma_f32_16x16x32_bf16 v[106:109], v[158:161], v[190:193], v[106:109]
	v_mfma_f32_16x16x32_bf16 v[106:109], v[162:165], v[194:197], v[106:109]
	v_mfma_f32_16x16x32_bf16 v[110:113], v[154:157], v[194:197], v[110:113]
	v_mfma_f32_16x16x32_bf16 v[110:113], v[150:153], v[190:193], v[110:113]
	v_mfma_f32_16x16x32_bf16 v[94:97], v[150:153], v[198:201], v[94:97]
	v_mfma_f32_16x16x32_bf16 v[94:97], v[154:157], v[202:205], v[94:97]
	v_mfma_f32_16x16x32_bf16 v[90:93], v[162:165], v[202:205], v[90:93]
	v_mfma_f32_16x16x32_bf16 v[90:93], v[158:161], v[198:201], v[90:93]
	v_mfma_f32_16x16x32_bf16 v[86:89], v[166:169], v[198:201], v[86:89]
	v_mfma_f32_16x16x32_bf16 v[86:89], v[170:173], v[202:205], v[86:89]
	v_mfma_f32_16x16x32_bf16 v[82:85], v[178:181], v[202:205], v[82:85]
	v_mfma_f32_16x16x32_bf16 v[82:85], v[174:177], v[198:201], v[82:85]
	v_mfma_f32_16x16x32_bf16 v[66:69], v[174:177], v[206:209], v[66:69]
	v_mfma_f32_16x16x32_bf16 v[66:69], v[178:181], v[210:213], v[66:69]
	v_mfma_f32_16x16x32_bf16 v[70:73], v[170:173], v[210:213], v[70:73]
	v_mfma_f32_16x16x32_bf16 v[70:73], v[166:169], v[206:209], v[70:73]
	v_mfma_f32_16x16x32_bf16 v[74:77], v[158:161], v[206:209], v[74:77]
	v_mfma_f32_16x16x32_bf16 v[74:77], v[162:165], v[210:213], v[74:77]
	v_mfma_f32_16x16x32_bf16 v[78:81], v[154:157], v[210:213], v[78:81]
	v_mfma_f32_16x16x32_bf16 v[78:81], v[150:153], v[206:209], v[78:81]
	s_barrier
	s_mov_b32 m0, s72
	v_lshl_add_u64 v[144:145], v[144:145], 0, s[4:5]
	ds_read_b128 v[182:185], v149 offset:49152
	ds_read_b128 v[186:189], v149 offset:50176
	ds_read_b128 v[190:193], v149 offset:51200
	ds_read_b128 v[194:197], v149 offset:52224
	ds_read_b128 v[198:201], v149 offset:53248
	ds_read_b128 v[202:205], v149 offset:54272
	ds_read_b128 v[206:209], v149 offset:55296
	ds_read_b128 v[210:213], v149 offset:56320
	global_load_lds_dwordx4 v[144:145], off
	s_add_i32 m0, s72, 0x2000
	s_add_u32 s22, s26, 0x18080
	v_lshl_add_u64 v[144:145], v[214:215], 0, s[4:5]
	s_addc_u32 s23, s27, 0
	s_add_i32 s26, s71, s30
	global_load_lds_dwordx4 v[144:145], off
	v_lshl_add_u64 v[144:145], s[22:23], 0, v[134:135]
	s_mov_b32 m0, s26
	s_nop 0
	global_load_lds_dwordx4 v[144:145], off
	v_lshl_add_u64 v[144:145], s[22:23], 0, v[130:131]
	s_add_i32 m0, s26, 0x2000
	s_nop 0
	global_load_lds_dwordx4 v[144:145], off
	v_lshl_add_u64 v[144:145], v[216:217], 0, s[4:5]
	s_mov_b32 m0, s59
	s_nop 0
	global_load_lds_dwordx4 v[144:145], off
	v_lshl_add_u64 v[144:145], v[218:219], 0, s[4:5]
	s_mov_b32 m0, s60
	s_nop 0
	global_load_lds_dwordx4 v[144:145], off
	s_waitcnt vmcnt(8)
	s_waitcnt lgkmcnt(0)
	s_barrier
	v_mfma_f32_16x16x32_bf16 v[62:65], v[150:153], v[182:185], v[62:65]
	v_mfma_f32_16x16x32_bf16 v[62:65], v[154:157], v[186:189], v[62:65]
	v_mfma_f32_16x16x32_bf16 v[58:61], v[162:165], v[186:189], v[58:61]
	v_mfma_f32_16x16x32_bf16 v[58:61], v[158:161], v[182:185], v[58:61]
	v_mfma_f32_16x16x32_bf16 v[54:57], v[166:169], v[182:185], v[54:57]
	v_mfma_f32_16x16x32_bf16 v[54:57], v[170:173], v[186:189], v[54:57]
	v_mfma_f32_16x16x32_bf16 v[50:53], v[178:181], v[186:189], v[50:53]
	v_mfma_f32_16x16x32_bf16 v[50:53], v[174:177], v[182:185], v[50:53]
	v_mfma_f32_16x16x32_bf16 v[34:37], v[174:177], v[190:193], v[34:37]
	v_mfma_f32_16x16x32_bf16 v[34:37], v[178:181], v[194:197], v[34:37]
	v_mfma_f32_16x16x32_bf16 v[38:41], v[170:173], v[194:197], v[38:41]
	v_mfma_f32_16x16x32_bf16 v[38:41], v[166:169], v[190:193], v[38:41]
	v_mfma_f32_16x16x32_bf16 v[42:45], v[158:161], v[190:193], v[42:45]
	v_mfma_f32_16x16x32_bf16 v[42:45], v[162:165], v[194:197], v[42:45]
	v_mfma_f32_16x16x32_bf16 v[46:49], v[154:157], v[194:197], v[46:49]
	v_mfma_f32_16x16x32_bf16 v[46:49], v[150:153], v[190:193], v[46:49]
	v_mfma_f32_16x16x32_bf16 v[30:33], v[150:153], v[198:201], v[30:33]
	v_mfma_f32_16x16x32_bf16 v[30:33], v[154:157], v[202:205], v[30:33]
	v_mfma_f32_16x16x32_bf16 v[26:29], v[162:165], v[202:205], v[26:29]
	v_mfma_f32_16x16x32_bf16 v[26:29], v[158:161], v[198:201], v[26:29]
	v_mfma_f32_16x16x32_bf16 v[22:25], v[166:169], v[198:201], v[22:25]
	v_mfma_f32_16x16x32_bf16 v[22:25], v[170:173], v[202:205], v[22:25]
	v_mfma_f32_16x16x32_bf16 v[18:21], v[178:181], v[202:205], v[18:21]
	v_mfma_f32_16x16x32_bf16 v[18:21], v[174:177], v[198:201], v[18:21]
	v_mfma_f32_16x16x32_bf16 v[2:5], v[174:177], v[206:209], v[2:5]
	v_mfma_f32_16x16x32_bf16 v[2:5], v[178:181], v[210:213], v[2:5]
	v_mfma_f32_16x16x32_bf16 v[6:9], v[170:173], v[210:213], v[6:9]
	v_mfma_f32_16x16x32_bf16 v[6:9], v[166:169], v[206:209], v[6:9]
	v_mfma_f32_16x16x32_bf16 v[10:13], v[158:161], v[206:209], v[10:13]
	v_mfma_f32_16x16x32_bf16 v[10:13], v[162:165], v[210:213], v[10:13]
	v_mfma_f32_16x16x32_bf16 v[14:17], v[154:157], v[210:213], v[14:17]
	v_mfma_f32_16x16x32_bf16 v[14:17], v[150:153], v[206:209], v[14:17]
	s_barrier
	s_add_u32 s75, s75, 0x100
	s_addc_u32 s76, s76, 0
	s_cmp_ge_i32 s77, s57
	s_mov_b64 s[22:23], s[24:25]
	s_mov_b32 s26, s77
	s_cbranch_scc0 .LBB0_468

.LBB0_599:
	v_add_u32_e32 v142, s74, v199
	v_add_u32_e32 v162, s75, v199
	ds_read_b128 v[130:133], v142
	ds_read_b128 v[134:137], v142 offset:1024
	ds_read_b128 v[138:141], v142 offset:2048
	ds_read_b128 v[142:145], v142 offset:3072
	ds_read_b128 v[146:149], v162
	ds_read_b128 v[150:153], v162 offset:1024
	ds_read_b128 v[174:177], v162 offset:2048
	ds_read_b128 v[178:181], v162 offset:3072
	s_add_i32 s31, s52, 2
	s_add_u32 s50, s34, 0x3ff000
	s_addc_u32 s51, s35, 0
	s_cmp_eq_u32 s71, s52
	s_cselect_b32 s56, s26, s50
	s_cselect_b32 s57, s27, s51
	s_cselect_b32 s54, s28, s23
	s_cselect_b32 s55, s29, s25
	s_add_u32 s52, s56, 0x400000
	s_addc_u32 s53, s57, 0
	v_lshl_add_u64 v[218:219], s[34:35], 0, v[164:165]
	s_add_i32 m0, s59, 0xc000
	ds_read_b128 v[182:185], v200
	ds_read_b128 v[186:189], v200 offset:1024
	ds_read_b128 v[190:193], v200 offset:2048
	ds_read_b128 v[194:197], v200 offset:3072
	ds_read_b128 v[202:205], v200 offset:4096
	ds_read_b128 v[206:209], v200 offset:5120
	ds_read_b128 v[210:213], v200 offset:6144
	ds_read_b128 v[214:217], v200 offset:7168
	global_load_lds_dwordx4 v[218:219], off
	v_lshl_add_u64 v[218:219], s[34:35], 0, v[166:167]
	s_add_i32 m0, s59, 0xe000
	s_nop 0
	global_load_lds_dwordx4 v[218:219], off
	s_waitcnt vmcnt(8)
	s_waitcnt lgkmcnt(0)
	s_barrier
	v_mfma_f32_16x16x32_bf16 v[118:121], v[130:133], v[182:185], v[118:121]
	v_mfma_f32_16x16x32_bf16 v[118:121], v[134:137], v[186:189], v[118:121]
	v_mfma_f32_16x16x32_bf16 v[122:125], v[142:145], v[186:189], v[122:125]
	v_mfma_f32_16x16x32_bf16 v[122:125], v[138:141], v[182:185], v[122:125]
	v_mfma_f32_16x16x32_bf16 v[126:129], v[146:149], v[182:185], v[126:129]
	v_mfma_f32_16x16x32_bf16 v[126:129], v[150:153], v[186:189], v[126:129]
	v_mfma_f32_16x16x32_bf16 v[114:117], v[178:181], v[186:189], v[114:117]
	v_mfma_f32_16x16x32_bf16 v[114:117], v[174:177], v[182:185], v[114:117]
	v_mfma_f32_16x16x32_bf16 v[98:101], v[174:177], v[190:193], v[98:101]
	v_mfma_f32_16x16x32_bf16 v[98:101], v[178:181], v[194:197], v[98:101]
	v_mfma_f32_16x16x32_bf16 v[102:105], v[150:153], v[194:197], v[102:105]
	v_mfma_f32_16x16x32_bf16 v[102:105], v[146:149], v[190:193], v[102:105]
	v_mfma_f32_16x16x32_bf16 v[106:109], v[138:141], v[190:193], v[106:109]
	v_mfma_f32_16x16x32_bf16 v[106:109], v[142:145], v[194:197], v[106:109]
	v_mfma_f32_16x16x32_bf16 v[110:113], v[134:137], v[194:197], v[110:113]
	v_mfma_f32_16x16x32_bf16 v[110:113], v[130:133], v[190:193], v[110:113]
	v_mfma_f32_16x16x32_bf16 v[94:97], v[130:133], v[202:205], v[94:97]
	v_mfma_f32_16x16x32_bf16 v[94:97], v[134:137], v[206:209], v[94:97]
	v_mfma_f32_16x16x32_bf16 v[90:93], v[142:145], v[206:209], v[90:93]
	v_mfma_f32_16x16x32_bf16 v[90:93], v[138:141], v[202:205], v[90:93]
	v_mfma_f32_16x16x32_bf16 v[86:89], v[146:149], v[202:205], v[86:89]
	v_mfma_f32_16x16x32_bf16 v[86:89], v[150:153], v[206:209], v[86:89]
	v_mfma_f32_16x16x32_bf16 v[82:85], v[178:181], v[206:209], v[82:85]
	v_mfma_f32_16x16x32_bf16 v[82:85], v[174:177], v[202:205], v[82:85]
	v_mfma_f32_16x16x32_bf16 v[66:69], v[174:177], v[210:213], v[66:69]
	v_mfma_f32_16x16x32_bf16 v[66:69], v[178:181], v[214:217], v[66:69]
	v_mfma_f32_16x16x32_bf16 v[70:73], v[150:153], v[214:217], v[70:73]
	v_mfma_f32_16x16x32_bf16 v[70:73], v[146:149], v[210:213], v[70:73]
	v_mfma_f32_16x16x32_bf16 v[74:77], v[138:141], v[210:213], v[74:77]
	v_mfma_f32_16x16x32_bf16 v[74:77], v[142:145], v[214:217], v[74:77]
	v_mfma_f32_16x16x32_bf16 v[78:81], v[134:137], v[214:217], v[78:81]
	v_mfma_f32_16x16x32_bf16 v[78:81], v[130:133], v[210:213], v[78:81]
	s_barrier
	s_add_i32 s50, s74, s41
	v_lshl_add_u64 v[218:219], s[54:55], 0, v[156:157]
	s_mov_b32 m0, s50
	ds_read_b128 v[182:185], v200 offset:16384
	ds_read_b128 v[186:189], v200 offset:17408
	ds_read_b128 v[190:193], v200 offset:18432
	ds_read_b128 v[194:197], v200 offset:19456
	ds_read_b128 v[202:205], v200 offset:20480
	ds_read_b128 v[206:209], v200 offset:21504
	ds_read_b128 v[210:213], v200 offset:22528
	ds_read_b128 v[214:217], v200 offset:23552
	global_load_lds_dwordx4 v[218:219], off
	s_add_i32 m0, s50, 0x2000
	s_add_u32 s50, s54, 0x20000
	v_lshl_add_u64 v[220:221], s[54:55], 0, v[160:161]
	s_addc_u32 s51, s55, 0
	s_add_i32 s78, s75, s41
	global_load_lds_dwordx4 v[220:221], off
	v_lshl_add_u64 v[222:223], s[50:51], 0, v[156:157]
	s_mov_b32 m0, s78
	s_nop 0
	global_load_lds_dwordx4 v[222:223], off
	v_lshl_add_u64 v[222:223], s[50:51], 0, v[160:161]
	s_add_i32 m0, s78, 0x2000
	s_nop 0
	global_load_lds_dwordx4 v[222:223], off
	v_lshl_add_u64 v[222:223], s[56:57], 0, v[154:155]
	s_mov_b32 m0, s59
	s_nop 0
	global_load_lds_dwordx4 v[222:223], off
	v_lshl_add_u64 v[222:223], s[56:57], 0, v[158:159]
	s_mov_b32 m0, s60
	s_nop 0
	global_load_lds_dwordx4 v[222:223], off
	s_waitcnt vmcnt(8)
	s_waitcnt lgkmcnt(0)
	s_barrier
	v_mfma_f32_16x16x32_bf16 v[62:65], v[130:133], v[182:185], v[62:65]
	v_mfma_f32_16x16x32_bf16 v[62:65], v[134:137], v[186:189], v[62:65]
	v_mfma_f32_16x16x32_bf16 v[58:61], v[142:145], v[186:189], v[58:61]
	v_mfma_f32_16x16x32_bf16 v[58:61], v[138:141], v[182:185], v[58:61]
	v_mfma_f32_16x16x32_bf16 v[54:57], v[146:149], v[182:185], v[54:57]
	v_mfma_f32_16x16x32_bf16 v[54:57], v[150:153], v[186:189], v[54:57]
	v_mfma_f32_16x16x32_bf16 v[50:53], v[178:181], v[186:189], v[50:53]
	v_mfma_f32_16x16x32_bf16 v[50:53], v[174:177], v[182:185], v[50:53]
	v_mfma_f32_16x16x32_bf16 v[34:37], v[174:177], v[190:193], v[34:37]
	v_mfma_f32_16x16x32_bf16 v[34:37], v[178:181], v[194:197], v[34:37]
	v_mfma_f32_16x16x32_bf16 v[38:41], v[150:153], v[194:197], v[38:41]
	v_mfma_f32_16x16x32_bf16 v[38:41], v[146:149], v[190:193], v[38:41]
	v_mfma_f32_16x16x32_bf16 v[42:45], v[138:141], v[190:193], v[42:45]
	v_mfma_f32_16x16x32_bf16 v[42:45], v[142:145], v[194:197], v[42:45]
	v_mfma_f32_16x16x32_bf16 v[46:49], v[134:137], v[194:197], v[46:49]
	v_mfma_f32_16x16x32_bf16 v[46:49], v[130:133], v[190:193], v[46:49]
	v_mfma_f32_16x16x32_bf16 v[30:33], v[130:133], v[202:205], v[30:33]
	v_mfma_f32_16x16x32_bf16 v[30:33], v[134:137], v[206:209], v[30:33]
	v_mfma_f32_16x16x32_bf16 v[26:29], v[142:145], v[206:209], v[26:29]
	v_mfma_f32_16x16x32_bf16 v[26:29], v[138:141], v[202:205], v[26:29]
	v_mfma_f32_16x16x32_bf16 v[22:25], v[146:149], v[202:205], v[22:25]
	v_mfma_f32_16x16x32_bf16 v[22:25], v[150:153], v[206:209], v[22:25]
	v_mfma_f32_16x16x32_bf16 v[18:21], v[178:181], v[206:209], v[18:21]
	v_mfma_f32_16x16x32_bf16 v[18:21], v[174:177], v[202:205], v[18:21]
	v_mfma_f32_16x16x32_bf16 v[2:5], v[174:177], v[210:213], v[2:5]
	v_mfma_f32_16x16x32_bf16 v[2:5], v[178:181], v[214:217], v[2:5]
	v_mfma_f32_16x16x32_bf16 v[6:9], v[150:153], v[214:217], v[6:9]
	v_mfma_f32_16x16x32_bf16 v[6:9], v[146:149], v[210:213], v[6:9]
	v_mfma_f32_16x16x32_bf16 v[10:13], v[138:141], v[210:213], v[10:13]
	v_mfma_f32_16x16x32_bf16 v[10:13], v[142:145], v[214:217], v[10:13]
	v_mfma_f32_16x16x32_bf16 v[14:17], v[134:137], v[214:217], v[14:17]
	v_mfma_f32_16x16x32_bf16 v[14:17], v[130:133], v[210:213], v[14:17]
	s_barrier
	s_add_i32 s78, 0, 0x18000
	s_add_i32 s79, 0, 0x1c000
	v_add_u32_e32 v142, s78, v199
	v_add_u32_e32 v162, s79, v199
	ds_read_b128 v[130:133], v142
	ds_read_b128 v[134:137], v142 offset:1024
	ds_read_b128 v[138:141], v142 offset:2048
	ds_read_b128 v[142:145], v142 offset:3072
	ds_read_b128 v[146:149], v162
	ds_read_b128 v[150:153], v162 offset:1024
	ds_read_b128 v[174:177], v162 offset:2048
	ds_read_b128 v[178:181], v162 offset:3072
	s_add_u32 s50, s56, 0x1000
	s_addc_u32 s51, s57, 0
	s_mov_b32 m0, s61
	v_lshl_add_u64 v[222:223], s[50:51], 0, v[154:155]
	ds_read_b128 v[182:185], v200 offset:32768
	ds_read_b128 v[186:189], v200 offset:33792
	ds_read_b128 v[190:193], v200 offset:34816
	ds_read_b128 v[194:197], v200 offset:35840
	ds_read_b128 v[202:205], v200 offset:36864
	ds_read_b128 v[206:209], v200 offset:37888
	ds_read_b128 v[210:213], v200 offset:38912
	ds_read_b128 v[214:217], v200 offset:39936
	global_load_lds_dwordx4 v[222:223], off
	v_lshl_add_u64 v[222:223], s[50:51], 0, v[158:159]
	s_mov_b32 m0, s62
	s_nop 0
	global_load_lds_dwordx4 v[222:223], off
	s_waitcnt vmcnt(8)
	s_waitcnt lgkmcnt(0)
	s_barrier
	v_mfma_f32_16x16x32_bf16 v[118:121], v[130:133], v[182:185], v[118:121]
	v_mfma_f32_16x16x32_bf16 v[118:121], v[134:137], v[186:189], v[118:121]
	v_mfma_f32_16x16x32_bf16 v[122:125], v[142:145], v[186:189], v[122:125]
	v_mfma_f32_16x16x32_bf16 v[122:125], v[138:141], v[182:185], v[122:125]
	v_mfma_f32_16x16x32_bf16 v[126:129], v[146:149], v[182:185], v[126:129]
	v_mfma_f32_16x16x32_bf16 v[126:129], v[150:153], v[186:189], v[126:129]
	v_mfma_f32_16x16x32_bf16 v[114:117], v[178:181], v[186:189], v[114:117]
	v_mfma_f32_16x16x32_bf16 v[114:117], v[174:177], v[182:185], v[114:117]
	v_mfma_f32_16x16x32_bf16 v[98:101], v[174:177], v[190:193], v[98:101]
	v_mfma_f32_16x16x32_bf16 v[98:101], v[178:181], v[194:197], v[98:101]
	v_mfma_f32_16x16x32_bf16 v[102:105], v[150:153], v[194:197], v[102:105]
	v_mfma_f32_16x16x32_bf16 v[102:105], v[146:149], v[190:193], v[102:105]
	v_mfma_f32_16x16x32_bf16 v[106:109], v[138:141], v[190:193], v[106:109]
	v_mfma_f32_16x16x32_bf16 v[106:109], v[142:145], v[194:197], v[106:109]
	v_mfma_f32_16x16x32_bf16 v[110:113], v[134:137], v[194:197], v[110:113]
	v_mfma_f32_16x16x32_bf16 v[110:113], v[130:133], v[190:193], v[110:113]
	v_mfma_f32_16x16x32_bf16 v[94:97], v[130:133], v[202:205], v[94:97]
	v_mfma_f32_16x16x32_bf16 v[94:97], v[134:137], v[206:209], v[94:97]
	v_mfma_f32_16x16x32_bf16 v[90:93], v[142:145], v[206:209], v[90:93]
	v_mfma_f32_16x16x32_bf16 v[90:93], v[138:141], v[202:205], v[90:93]
	v_mfma_f32_16x16x32_bf16 v[86:89], v[146:149], v[202:205], v[86:89]
	v_mfma_f32_16x16x32_bf16 v[86:89], v[150:153], v[206:209], v[86:89]
	v_mfma_f32_16x16x32_bf16 v[82:85], v[178:181], v[206:209], v[82:85]
	v_mfma_f32_16x16x32_bf16 v[82:85], v[174:177], v[202:205], v[82:85]
	v_mfma_f32_16x16x32_bf16 v[66:69], v[174:177], v[210:213], v[66:69]
	v_mfma_f32_16x16x32_bf16 v[66:69], v[178:181], v[214:217], v[66:69]
	v_mfma_f32_16x16x32_bf16 v[70:73], v[150:153], v[214:217], v[70:73]
	v_mfma_f32_16x16x32_bf16 v[70:73], v[146:149], v[210:213], v[70:73]
	v_mfma_f32_16x16x32_bf16 v[74:77], v[138:141], v[210:213], v[74:77]
	v_mfma_f32_16x16x32_bf16 v[74:77], v[142:145], v[214:217], v[74:77]
	v_mfma_f32_16x16x32_bf16 v[78:81], v[134:137], v[214:217], v[78:81]
	v_mfma_f32_16x16x32_bf16 v[78:81], v[130:133], v[210:213], v[78:81]
	s_barrier
	s_add_i32 s50, s78, s41
	v_lshl_add_u64 v[218:219], v[218:219], 0, s[14:15]
	s_mov_b32 m0, s50
	ds_read_b128 v[182:185], v200 offset:49152
	ds_read_b128 v[186:189], v200 offset:50176
	ds_read_b128 v[190:193], v200 offset:51200
	ds_read_b128 v[194:197], v200 offset:52224
	ds_read_b128 v[202:205], v200 offset:53248
	ds_read_b128 v[206:209], v200 offset:54272
	ds_read_b128 v[210:213], v200 offset:55296
	ds_read_b128 v[214:217], v200 offset:56320
	global_load_lds_dwordx4 v[218:219], off
	s_add_i32 m0, s50, 0x2000
	s_add_u32 s50, s54, 0x20080
	v_lshl_add_u64 v[218:219], v[220:221], 0, s[14:15]
	s_addc_u32 s51, s55, 0
	s_add_i32 s54, s79, s41
	global_load_lds_dwordx4 v[218:219], off
	v_lshl_add_u64 v[218:219], s[50:51], 0, v[156:157]
	s_mov_b32 m0, s54
	s_nop 0
	global_load_lds_dwordx4 v[218:219], off
	v_lshl_add_u64 v[218:219], s[50:51], 0, v[160:161]
	s_add_i32 m0, s54, 0x2000
	s_nop 0
	global_load_lds_dwordx4 v[218:219], off
	v_lshl_add_u64 v[218:219], s[52:53], 0, v[154:155]
	s_mov_b32 m0, s69
	s_nop 0
	global_load_lds_dwordx4 v[218:219], off
	v_lshl_add_u64 v[218:219], s[52:53], 0, v[158:159]
	s_mov_b32 m0, s70
	s_nop 0
	global_load_lds_dwordx4 v[218:219], off
	s_waitcnt vmcnt(8)
	s_waitcnt lgkmcnt(0)
	s_barrier
	v_mfma_f32_16x16x32_bf16 v[62:65], v[130:133], v[182:185], v[62:65]
	v_mfma_f32_16x16x32_bf16 v[62:65], v[134:137], v[186:189], v[62:65]
	v_mfma_f32_16x16x32_bf16 v[58:61], v[142:145], v[186:189], v[58:61]
	v_mfma_f32_16x16x32_bf16 v[58:61], v[138:141], v[182:185], v[58:61]
	v_mfma_f32_16x16x32_bf16 v[54:57], v[146:149], v[182:185], v[54:57]
	v_mfma_f32_16x16x32_bf16 v[54:57], v[150:153], v[186:189], v[54:57]
	v_mfma_f32_16x16x32_bf16 v[50:53], v[178:181], v[186:189], v[50:53]
	v_mfma_f32_16x16x32_bf16 v[50:53], v[174:177], v[182:185], v[50:53]
	v_mfma_f32_16x16x32_bf16 v[34:37], v[174:177], v[190:193], v[34:37]
	v_mfma_f32_16x16x32_bf16 v[34:37], v[178:181], v[194:197], v[34:37]
	v_mfma_f32_16x16x32_bf16 v[38:41], v[150:153], v[194:197], v[38:41]
	v_mfma_f32_16x16x32_bf16 v[38:41], v[146:149], v[190:193], v[38:41]
	v_mfma_f32_16x16x32_bf16 v[42:45], v[138:141], v[190:193], v[42:45]
	v_mfma_f32_16x16x32_bf16 v[42:45], v[142:145], v[194:197], v[42:45]
	v_mfma_f32_16x16x32_bf16 v[46:49], v[134:137], v[194:197], v[46:49]
	v_mfma_f32_16x16x32_bf16 v[46:49], v[130:133], v[190:193], v[46:49]
	v_mfma_f32_16x16x32_bf16 v[30:33], v[130:133], v[202:205], v[30:33]
	v_mfma_f32_16x16x32_bf16 v[30:33], v[134:137], v[206:209], v[30:33]
	v_mfma_f32_16x16x32_bf16 v[26:29], v[142:145], v[206:209], v[26:29]
	v_mfma_f32_16x16x32_bf16 v[26:29], v[138:141], v[202:205], v[26:29]
	v_mfma_f32_16x16x32_bf16 v[22:25], v[146:149], v[202:205], v[22:25]
	v_mfma_f32_16x16x32_bf16 v[22:25], v[150:153], v[206:209], v[22:25]
	v_mfma_f32_16x16x32_bf16 v[18:21], v[178:181], v[206:209], v[18:21]
	v_mfma_f32_16x16x32_bf16 v[18:21], v[174:177], v[202:205], v[18:21]
	v_mfma_f32_16x16x32_bf16 v[2:5], v[174:177], v[210:213], v[2:5]
	v_mfma_f32_16x16x32_bf16 v[2:5], v[178:181], v[214:217], v[2:5]
	v_mfma_f32_16x16x32_bf16 v[6:9], v[150:153], v[214:217], v[6:9]
	v_mfma_f32_16x16x32_bf16 v[6:9], v[146:149], v[210:213], v[6:9]
	v_mfma_f32_16x16x32_bf16 v[10:13], v[138:141], v[210:213], v[10:13]
	v_mfma_f32_16x16x32_bf16 v[10:13], v[142:145], v[214:217], v[10:13]
	v_mfma_f32_16x16x32_bf16 v[14:17], v[134:137], v[214:217], v[14:17]
	v_mfma_f32_16x16x32_bf16 v[14:17], v[130:133], v[210:213], v[14:17]
	s_barrier
	s_add_u32 s23, s23, 0x100
	s_addc_u32 s25, s25, 0
	s_add_u32 s34, s34, 0x800000
	s_addc_u32 s35, s35, 0
	s_cmp_ge_i32 s31, s67
	s_mov_b32 s52, s31
	s_cbranch_scc0 .LBB0_599

.LBB0_740:
	v_add_u32_e32 v144, s88, v188
	v_add_u32_e32 v160, s89, v188
	ds_read_b128 v[132:135], v144
	ds_read_b128 v[136:139], v144 offset:1024
	ds_read_b128 v[140:143], v144 offset:2048
	ds_read_b128 v[144:147], v144 offset:3072
	ds_read_b128 v[148:151], v160
	ds_read_b128 v[152:155], v160 offset:1024
	ds_read_b128 v[156:159], v160 offset:2048
	ds_read_b128 v[184:187], v160 offset:3072
	s_add_i32 s92, s55, 2
	s_add_u32 s50, s60, 0x3fc000
	s_addc_u32 s51, s61, 0
	s_cmp_eq_u32 s87, s55
	s_cselect_b32 s70, s64, s50
	s_cselect_b32 s71, s65, s51
	s_cselect_b32 s69, s67, s53
	s_cselect_b32 s68, s66, s13
	s_add_u32 s62, s70, 0x400000
	s_addc_u32 s63, s71, 0
	v_lshl_add_u64 v[160:161], s[60:61], 0, v[176:177]
	s_add_i32 m0, s77, 0xc000
	ds_read_b128 v[192:195], v189
	ds_read_b128 v[196:199], v189 offset:1024
	ds_read_b128 v[200:203], v189 offset:2048
	ds_read_b128 v[204:207], v189 offset:3072
	ds_read_b128 v[208:211], v189 offset:4096
	ds_read_b128 v[212:215], v189 offset:5120
	ds_read_b128 v[216:219], v189 offset:6144
	ds_read_b128 v[220:223], v189 offset:7168
	global_load_lds_dwordx4 v[160:161], off
	v_lshl_add_u64 v[160:161], s[60:61], 0, v[178:179]
	s_add_i32 m0, s77, 0xe000
	s_nop 0
	global_load_lds_dwordx4 v[160:161], off
	s_waitcnt vmcnt(8)
	s_waitcnt lgkmcnt(0)
	s_barrier
	v_mfma_f32_16x16x32_bf16 v[30:33], v[132:135], v[192:195], v[30:33]
	v_mfma_f32_16x16x32_bf16 v[30:33], v[136:139], v[196:199], v[30:33]
	v_mfma_f32_16x16x32_bf16 v[26:29], v[144:147], v[196:199], v[26:29]
	v_mfma_f32_16x16x32_bf16 v[26:29], v[140:143], v[192:195], v[26:29]
	v_mfma_f32_16x16x32_bf16 v[50:53], v[148:151], v[192:195], v[50:53]
	v_mfma_f32_16x16x32_bf16 v[50:53], v[152:155], v[196:199], v[50:53]
	v_mfma_f32_16x16x32_bf16 v[42:45], v[184:187], v[196:199], v[42:45]
	v_mfma_f32_16x16x32_bf16 v[42:45], v[156:159], v[192:195], v[42:45]
	v_mfma_f32_16x16x32_bf16 v[2:5], v[156:159], v[200:203], v[2:5]
	v_mfma_f32_16x16x32_bf16 v[2:5], v[184:187], v[204:207], v[2:5]
	v_mfma_f32_16x16x32_bf16 v[14:17], v[152:155], v[204:207], v[14:17]
	v_mfma_f32_16x16x32_bf16 v[14:17], v[148:151], v[200:203], v[14:17]
	v_mfma_f32_16x16x32_bf16 v[66:69], v[140:143], v[200:203], v[66:69]
	v_mfma_f32_16x16x32_bf16 v[66:69], v[144:147], v[204:207], v[66:69]
	v_mfma_f32_16x16x32_bf16 v[86:89], v[136:139], v[204:207], v[86:89]
	v_mfma_f32_16x16x32_bf16 v[86:89], v[132:135], v[200:203], v[86:89]
	v_mfma_f32_16x16x32_bf16 v[94:97], v[132:135], v[208:211], v[94:97]
	v_mfma_f32_16x16x32_bf16 v[94:97], v[136:139], v[212:215], v[94:97]
	v_mfma_f32_16x16x32_bf16 v[82:85], v[144:147], v[212:215], v[82:85]
	v_mfma_f32_16x16x32_bf16 v[82:85], v[140:143], v[208:211], v[82:85]
	v_mfma_f32_16x16x32_bf16 v[22:25], v[148:151], v[208:211], v[22:25]
	v_mfma_f32_16x16x32_bf16 v[22:25], v[152:155], v[212:215], v[22:25]
	v_mfma_f32_16x16x32_bf16 v[10:13], v[184:187], v[212:215], v[10:13]
	v_mfma_f32_16x16x32_bf16 v[10:13], v[156:159], v[208:211], v[10:13]
	v_mfma_f32_16x16x32_bf16 v[6:9], v[156:159], v[216:219], v[6:9]
	v_mfma_f32_16x16x32_bf16 v[6:9], v[184:187], v[220:223], v[6:9]
	v_mfma_f32_16x16x32_bf16 v[18:21], v[152:155], v[220:223], v[18:21]
	v_mfma_f32_16x16x32_bf16 v[18:21], v[148:151], v[216:219], v[18:21]
	v_mfma_f32_16x16x32_bf16 v[78:81], v[140:143], v[216:219], v[78:81]
	v_mfma_f32_16x16x32_bf16 v[78:81], v[144:147], v[220:223], v[78:81]
	v_mfma_f32_16x16x32_bf16 v[90:93], v[136:139], v[220:223], v[90:93]
	v_mfma_f32_16x16x32_bf16 v[90:93], v[132:135], v[216:219], v[90:93]
	s_barrier
	s_add_i32 s50, s88, s76
	v_lshl_add_u64 v[160:161], s[68:69], 0, v[164:165]
	s_mov_b32 m0, s50
	ds_read_b128 v[192:195], v189 offset:16384
	ds_read_b128 v[196:199], v189 offset:17408
	ds_read_b128 v[200:203], v189 offset:18432
	ds_read_b128 v[204:207], v189 offset:19456
	ds_read_b128 v[208:211], v189 offset:20480
	ds_read_b128 v[212:215], v189 offset:21504
	ds_read_b128 v[216:219], v189 offset:22528
	ds_read_b128 v[220:223], v189 offset:23552
	global_load_lds_dwordx4 v[160:161], off
	s_add_i32 m0, s50, 0x2000
	s_add_u32 s50, s68, 0x10000
	v_lshl_add_u64 v[224:225], s[68:69], 0, v[168:169]
	s_addc_u32 s51, s69, 0
	s_add_i32 s55, s89, s76
	global_load_lds_dwordx4 v[224:225], off
	v_lshl_add_u64 v[226:227], s[50:51], 0, v[164:165]
	s_mov_b32 m0, s55
	s_nop 0
	global_load_lds_dwordx4 v[226:227], off
	v_lshl_add_u64 v[226:227], s[50:51], 0, v[168:169]
	s_add_i32 m0, s55, 0x2000
	s_nop 0
	global_load_lds_dwordx4 v[226:227], off
	v_lshl_add_u64 v[226:227], s[70:71], 0, v[162:163]
	s_mov_b32 m0, s77
	s_nop 0
	global_load_lds_dwordx4 v[226:227], off
	v_lshl_add_u64 v[226:227], s[70:71], 0, v[166:167]
	s_mov_b32 m0, s78
	s_nop 0
	global_load_lds_dwordx4 v[226:227], off
	s_waitcnt vmcnt(8)
	s_waitcnt lgkmcnt(0)
	s_barrier
	v_mfma_f32_16x16x32_bf16 v[118:121], v[132:135], v[192:195], v[118:121]
	v_mfma_f32_16x16x32_bf16 v[118:121], v[136:139], v[196:199], v[118:121]
	v_mfma_f32_16x16x32_bf16 v[102:105], v[144:147], v[196:199], v[102:105]
	v_mfma_f32_16x16x32_bf16 v[102:105], v[140:143], v[192:195], v[102:105]
	v_mfma_f32_16x16x32_bf16 v[62:65], v[148:151], v[192:195], v[62:65]
	v_mfma_f32_16x16x32_bf16 v[62:65], v[152:155], v[196:199], v[62:65]
	v_mfma_f32_16x16x32_bf16 v[38:41], v[184:187], v[196:199], v[38:41]
	v_mfma_f32_16x16x32_bf16 v[38:41], v[156:159], v[192:195], v[38:41]
	v_mfma_f32_16x16x32_bf16 v[34:37], v[156:159], v[200:203], v[34:37]
	v_mfma_f32_16x16x32_bf16 v[34:37], v[184:187], v[204:207], v[34:37]
	v_mfma_f32_16x16x32_bf16 v[58:61], v[152:155], v[204:207], v[58:61]
	v_mfma_f32_16x16x32_bf16 v[58:61], v[148:151], v[200:203], v[58:61]
	v_mfma_f32_16x16x32_bf16 v[98:101], v[140:143], v[200:203], v[98:101]
	v_mfma_f32_16x16x32_bf16 v[98:101], v[144:147], v[204:207], v[98:101]
	v_mfma_f32_16x16x32_bf16 v[114:117], v[136:139], v[204:207], v[114:117]
	v_mfma_f32_16x16x32_bf16 v[114:117], v[132:135], v[200:203], v[114:117]
	v_mfma_f32_16x16x32_bf16 v[126:129], v[132:135], v[208:211], v[126:129]
	v_mfma_f32_16x16x32_bf16 v[126:129], v[136:139], v[212:215], v[126:129]
	v_mfma_f32_16x16x32_bf16 v[110:113], v[144:147], v[212:215], v[110:113]
	v_mfma_f32_16x16x32_bf16 v[110:113], v[140:143], v[208:211], v[110:113]
	v_mfma_f32_16x16x32_bf16 v[74:77], v[148:151], v[208:211], v[74:77]
	v_mfma_f32_16x16x32_bf16 v[74:77], v[152:155], v[212:215], v[74:77]
	v_mfma_f32_16x16x32_bf16 v[54:57], v[184:187], v[212:215], v[54:57]
	v_mfma_f32_16x16x32_bf16 v[54:57], v[156:159], v[208:211], v[54:57]
	v_mfma_f32_16x16x32_bf16 v[46:49], v[156:159], v[216:219], v[46:49]
	v_mfma_f32_16x16x32_bf16 v[46:49], v[184:187], v[220:223], v[46:49]
	v_mfma_f32_16x16x32_bf16 v[70:73], v[152:155], v[220:223], v[70:73]
	v_mfma_f32_16x16x32_bf16 v[70:73], v[148:151], v[216:219], v[70:73]
	v_mfma_f32_16x16x32_bf16 v[106:109], v[140:143], v[216:219], v[106:109]
	v_mfma_f32_16x16x32_bf16 v[106:109], v[144:147], v[220:223], v[106:109]
	v_mfma_f32_16x16x32_bf16 v[122:125], v[136:139], v[220:223], v[122:125]
	v_mfma_f32_16x16x32_bf16 v[122:125], v[132:135], v[216:219], v[122:125]
	s_barrier
	s_add_i32 s55, 0, 0x18000
	s_add_i32 s93, 0, 0x1c000
	v_add_u32_e32 v144, s55, v188
	v_add_u32_e32 v184, s93, v188
	ds_read_b128 v[132:135], v144
	ds_read_b128 v[136:139], v144 offset:1024
	ds_read_b128 v[140:143], v144 offset:2048
	ds_read_b128 v[144:147], v144 offset:3072
	ds_read_b128 v[148:151], v184
	ds_read_b128 v[152:155], v184 offset:1024
	ds_read_b128 v[156:159], v184 offset:2048
	ds_read_b128 v[184:187], v184 offset:3072
	s_add_u32 s50, s70, 0x4000
	s_addc_u32 s51, s71, 0
	s_mov_b32 m0, s79
	v_lshl_add_u64 v[226:227], s[50:51], 0, v[162:163]
	ds_read_b128 v[192:195], v189 offset:32768
	ds_read_b128 v[196:199], v189 offset:33792
	ds_read_b128 v[200:203], v189 offset:34816
	ds_read_b128 v[204:207], v189 offset:35840
	ds_read_b128 v[208:211], v189 offset:36864
	ds_read_b128 v[212:215], v189 offset:37888
	ds_read_b128 v[216:219], v189 offset:38912
	ds_read_b128 v[220:223], v189 offset:39936
	global_load_lds_dwordx4 v[226:227], off
	v_lshl_add_u64 v[226:227], s[50:51], 0, v[166:167]
	s_mov_b32 m0, s80
	s_nop 0
	global_load_lds_dwordx4 v[226:227], off
	s_waitcnt vmcnt(8)
	s_waitcnt lgkmcnt(0)
	s_barrier
	v_mfma_f32_16x16x32_bf16 v[30:33], v[132:135], v[192:195], v[30:33]
	v_mfma_f32_16x16x32_bf16 v[30:33], v[136:139], v[196:199], v[30:33]
	v_mfma_f32_16x16x32_bf16 v[26:29], v[144:147], v[196:199], v[26:29]
	v_mfma_f32_16x16x32_bf16 v[26:29], v[140:143], v[192:195], v[26:29]
	v_mfma_f32_16x16x32_bf16 v[50:53], v[148:151], v[192:195], v[50:53]
	v_mfma_f32_16x16x32_bf16 v[50:53], v[152:155], v[196:199], v[50:53]
	v_mfma_f32_16x16x32_bf16 v[42:45], v[184:187], v[196:199], v[42:45]
	v_mfma_f32_16x16x32_bf16 v[42:45], v[156:159], v[192:195], v[42:45]
	v_mfma_f32_16x16x32_bf16 v[2:5], v[156:159], v[200:203], v[2:5]
	v_mfma_f32_16x16x32_bf16 v[2:5], v[184:187], v[204:207], v[2:5]
	v_mfma_f32_16x16x32_bf16 v[14:17], v[152:155], v[204:207], v[14:17]
	v_mfma_f32_16x16x32_bf16 v[14:17], v[148:151], v[200:203], v[14:17]
	v_mfma_f32_16x16x32_bf16 v[66:69], v[140:143], v[200:203], v[66:69]
	v_mfma_f32_16x16x32_bf16 v[66:69], v[144:147], v[204:207], v[66:69]
	v_mfma_f32_16x16x32_bf16 v[86:89], v[136:139], v[204:207], v[86:89]
	v_mfma_f32_16x16x32_bf16 v[86:89], v[132:135], v[200:203], v[86:89]
	v_mfma_f32_16x16x32_bf16 v[94:97], v[132:135], v[208:211], v[94:97]
	v_mfma_f32_16x16x32_bf16 v[94:97], v[136:139], v[212:215], v[94:97]
	v_mfma_f32_16x16x32_bf16 v[82:85], v[144:147], v[212:215], v[82:85]
	v_mfma_f32_16x16x32_bf16 v[82:85], v[140:143], v[208:211], v[82:85]
	v_mfma_f32_16x16x32_bf16 v[22:25], v[148:151], v[208:211], v[22:25]
	v_mfma_f32_16x16x32_bf16 v[22:25], v[152:155], v[212:215], v[22:25]
	v_mfma_f32_16x16x32_bf16 v[10:13], v[184:187], v[212:215], v[10:13]
	v_mfma_f32_16x16x32_bf16 v[10:13], v[156:159], v[208:211], v[10:13]
	v_mfma_f32_16x16x32_bf16 v[6:9], v[156:159], v[216:219], v[6:9]
	v_mfma_f32_16x16x32_bf16 v[6:9], v[184:187], v[220:223], v[6:9]
	v_mfma_f32_16x16x32_bf16 v[18:21], v[152:155], v[220:223], v[18:21]
	v_mfma_f32_16x16x32_bf16 v[18:21], v[148:151], v[216:219], v[18:21]
	v_mfma_f32_16x16x32_bf16 v[78:81], v[140:143], v[216:219], v[78:81]
	v_mfma_f32_16x16x32_bf16 v[78:81], v[144:147], v[220:223], v[78:81]
	v_mfma_f32_16x16x32_bf16 v[90:93], v[136:139], v[220:223], v[90:93]
	v_mfma_f32_16x16x32_bf16 v[90:93], v[132:135], v[216:219], v[90:93]
	s_barrier
	s_add_i32 s50, s55, s76
	v_lshl_add_u64 v[160:161], v[160:161], 0, s[14:15]
	s_mov_b32 m0, s50
	ds_read_b128 v[192:195], v189 offset:49152
	ds_read_b128 v[196:199], v189 offset:50176
	ds_read_b128 v[200:203], v189 offset:51200
	ds_read_b128 v[204:207], v189 offset:52224
	ds_read_b128 v[208:211], v189 offset:53248
	ds_read_b128 v[212:215], v189 offset:54272
	ds_read_b128 v[216:219], v189 offset:55296
	ds_read_b128 v[220:223], v189 offset:56320
	global_load_lds_dwordx4 v[160:161], off
	s_add_i32 m0, s50, 0x2000
	s_add_u32 s50, s68, 0x10080
	v_lshl_add_u64 v[160:161], v[224:225], 0, s[14:15]
	s_addc_u32 s51, s69, 0
	s_add_i32 s55, s93, s76
	global_load_lds_dwordx4 v[160:161], off
	v_lshl_add_u64 v[160:161], s[50:51], 0, v[164:165]
	s_mov_b32 m0, s55
	s_nop 0
	global_load_lds_dwordx4 v[160:161], off
	v_lshl_add_u64 v[160:161], s[50:51], 0, v[168:169]
	s_add_i32 m0, s55, 0x2000
	s_nop 0
	global_load_lds_dwordx4 v[160:161], off
	v_lshl_add_u64 v[160:161], s[62:63], 0, v[162:163]
	s_mov_b32 m0, s84
	s_nop 0
	global_load_lds_dwordx4 v[160:161], off
	v_lshl_add_u64 v[160:161], s[62:63], 0, v[166:167]
	s_mov_b32 m0, s85
	s_nop 0
	global_load_lds_dwordx4 v[160:161], off
	s_waitcnt vmcnt(8)
	s_waitcnt lgkmcnt(0)
	s_barrier
	v_mfma_f32_16x16x32_bf16 v[118:121], v[132:135], v[192:195], v[118:121]
	v_mfma_f32_16x16x32_bf16 v[118:121], v[136:139], v[196:199], v[118:121]
	v_mfma_f32_16x16x32_bf16 v[102:105], v[144:147], v[196:199], v[102:105]
	v_mfma_f32_16x16x32_bf16 v[102:105], v[140:143], v[192:195], v[102:105]
	v_mfma_f32_16x16x32_bf16 v[62:65], v[148:151], v[192:195], v[62:65]
	v_mfma_f32_16x16x32_bf16 v[62:65], v[152:155], v[196:199], v[62:65]
	v_mfma_f32_16x16x32_bf16 v[38:41], v[184:187], v[196:199], v[38:41]
	v_mfma_f32_16x16x32_bf16 v[38:41], v[156:159], v[192:195], v[38:41]
	v_mfma_f32_16x16x32_bf16 v[34:37], v[156:159], v[200:203], v[34:37]
	v_mfma_f32_16x16x32_bf16 v[34:37], v[184:187], v[204:207], v[34:37]
	v_mfma_f32_16x16x32_bf16 v[58:61], v[152:155], v[204:207], v[58:61]
	v_mfma_f32_16x16x32_bf16 v[58:61], v[148:151], v[200:203], v[58:61]
	v_mfma_f32_16x16x32_bf16 v[98:101], v[140:143], v[200:203], v[98:101]
	v_mfma_f32_16x16x32_bf16 v[98:101], v[144:147], v[204:207], v[98:101]
	v_mfma_f32_16x16x32_bf16 v[114:117], v[136:139], v[204:207], v[114:117]
	v_mfma_f32_16x16x32_bf16 v[114:117], v[132:135], v[200:203], v[114:117]
	v_mfma_f32_16x16x32_bf16 v[126:129], v[132:135], v[208:211], v[126:129]
	v_mfma_f32_16x16x32_bf16 v[126:129], v[136:139], v[212:215], v[126:129]
	v_mfma_f32_16x16x32_bf16 v[110:113], v[144:147], v[212:215], v[110:113]
	v_mfma_f32_16x16x32_bf16 v[110:113], v[140:143], v[208:211], v[110:113]
	v_mfma_f32_16x16x32_bf16 v[74:77], v[148:151], v[208:211], v[74:77]
	v_mfma_f32_16x16x32_bf16 v[74:77], v[152:155], v[212:215], v[74:77]
	v_mfma_f32_16x16x32_bf16 v[54:57], v[184:187], v[212:215], v[54:57]
	v_mfma_f32_16x16x32_bf16 v[54:57], v[156:159], v[208:211], v[54:57]
	v_mfma_f32_16x16x32_bf16 v[46:49], v[156:159], v[216:219], v[46:49]
	v_mfma_f32_16x16x32_bf16 v[46:49], v[184:187], v[220:223], v[46:49]
	v_mfma_f32_16x16x32_bf16 v[70:73], v[152:155], v[220:223], v[70:73]
	v_mfma_f32_16x16x32_bf16 v[70:73], v[148:151], v[216:219], v[70:73]
	v_mfma_f32_16x16x32_bf16 v[106:109], v[140:143], v[216:219], v[106:109]
	v_mfma_f32_16x16x32_bf16 v[106:109], v[144:147], v[220:223], v[106:109]
	v_mfma_f32_16x16x32_bf16 v[122:125], v[136:139], v[220:223], v[122:125]
	v_mfma_f32_16x16x32_bf16 v[122:125], v[132:135], v[216:219], v[122:125]
	s_barrier
	s_add_u32 s13, s13, 0x100
	s_addc_u32 s53, s53, 0
	s_add_u32 s60, s60, 0x800000
	s_addc_u32 s61, s61, 0
	s_cmp_ge_i32 s92, s83
	s_cbranch_scc0 .LBB0_738

.LBB0_872:
	v_add_u32_e32 v162, s73, v140
	v_add_u32_e32 v178, s74, v140
	ds_read_b128 v[150:153], v162
	ds_read_b128 v[154:157], v162 offset:1024
	ds_read_b128 v[158:161], v162 offset:2048
	ds_read_b128 v[162:165], v162 offset:3072
	ds_read_b128 v[166:169], v178
	ds_read_b128 v[170:173], v178 offset:1024
	ds_read_b128 v[174:177], v178 offset:2048
	ds_read_b128 v[178:181], v178 offset:3072
	s_add_i32 s77, s52, 2
	s_add_u32 s50, s34, 0xfffc0080
	s_addc_u32 s51, s35, -1
	s_cmp_eq_u32 s70, s52
	s_cselect_b32 s52, s30, s21
	s_cselect_b32 s55, s29, s51
	s_cselect_b32 s54, s28, s50
	s_cselect_b32 s53, s31, s23
	v_lshl_add_u64 v[214:215], s[34:35], 0, v[132:133]
	s_add_i32 m0, s60, 0xc000
	ds_read_b128 v[182:185], v149
	ds_read_b128 v[186:189], v149 offset:1024
	ds_read_b128 v[190:193], v149 offset:2048
	ds_read_b128 v[194:197], v149 offset:3072
	ds_read_b128 v[198:201], v149 offset:4096
	ds_read_b128 v[202:205], v149 offset:5120
	ds_read_b128 v[206:209], v149 offset:6144
	ds_read_b128 v[210:213], v149 offset:7168
	global_load_lds_dwordx4 v[214:215], off
	v_lshl_add_u64 v[214:215], s[34:35], 0, v[134:135]
	s_add_i32 m0, s60, 0xe000
	s_nop 0
	global_load_lds_dwordx4 v[214:215], off
	s_waitcnt vmcnt(8)
	s_waitcnt lgkmcnt(0)
	s_barrier
	v_mfma_f32_16x16x32_bf16 v[78:81], v[150:153], v[182:185], v[78:81]
	v_mfma_f32_16x16x32_bf16 v[78:81], v[154:157], v[186:189], v[78:81]
	v_mfma_f32_16x16x32_bf16 v[14:17], v[162:165], v[186:189], v[14:17]
	v_mfma_f32_16x16x32_bf16 v[14:17], v[158:161], v[182:185], v[14:17]
	v_mfma_f32_16x16x32_bf16 v[98:101], v[166:169], v[182:185], v[98:101]
	v_mfma_f32_16x16x32_bf16 v[98:101], v[170:173], v[186:189], v[98:101]
	v_mfma_f32_16x16x32_bf16 v[34:37], v[178:181], v[186:189], v[34:37]
	v_mfma_f32_16x16x32_bf16 v[34:37], v[174:177], v[182:185], v[34:37]
	v_mfma_f32_16x16x32_bf16 v[18:21], v[174:177], v[190:193], v[18:21]
	v_mfma_f32_16x16x32_bf16 v[18:21], v[178:181], v[194:197], v[18:21]
	v_mfma_f32_16x16x32_bf16 v[82:85], v[170:173], v[194:197], v[82:85]
	v_mfma_f32_16x16x32_bf16 v[82:85], v[166:169], v[190:193], v[82:85]
	v_mfma_f32_16x16x32_bf16 v[2:5], v[158:161], v[190:193], v[2:5]
	v_mfma_f32_16x16x32_bf16 v[2:5], v[162:165], v[194:197], v[2:5]
	v_mfma_f32_16x16x32_bf16 v[66:69], v[154:157], v[194:197], v[66:69]
	v_mfma_f32_16x16x32_bf16 v[66:69], v[150:153], v[190:193], v[66:69]
	v_mfma_f32_16x16x32_bf16 v[70:73], v[150:153], v[198:201], v[70:73]
	v_mfma_f32_16x16x32_bf16 v[70:73], v[154:157], v[202:205], v[70:73]
	v_mfma_f32_16x16x32_bf16 v[6:9], v[162:165], v[202:205], v[6:9]
	v_mfma_f32_16x16x32_bf16 v[6:9], v[158:161], v[198:201], v[6:9]
	v_mfma_f32_16x16x32_bf16 v[86:89], v[166:169], v[198:201], v[86:89]
	v_mfma_f32_16x16x32_bf16 v[86:89], v[170:173], v[202:205], v[86:89]
	v_mfma_f32_16x16x32_bf16 v[22:25], v[178:181], v[202:205], v[22:25]
	v_mfma_f32_16x16x32_bf16 v[22:25], v[174:177], v[198:201], v[22:25]
	v_mfma_f32_16x16x32_bf16 v[30:33], v[174:177], v[206:209], v[30:33]
	v_mfma_f32_16x16x32_bf16 v[30:33], v[178:181], v[210:213], v[30:33]
	v_mfma_f32_16x16x32_bf16 v[94:97], v[170:173], v[210:213], v[94:97]
	v_mfma_f32_16x16x32_bf16 v[94:97], v[166:169], v[206:209], v[94:97]
	v_mfma_f32_16x16x32_bf16 v[10:13], v[158:161], v[206:209], v[10:13]
	v_mfma_f32_16x16x32_bf16 v[10:13], v[162:165], v[210:213], v[10:13]
	v_mfma_f32_16x16x32_bf16 v[74:77], v[154:157], v[210:213], v[74:77]
	v_mfma_f32_16x16x32_bf16 v[74:77], v[150:153], v[206:209], v[74:77]
	s_barrier
	s_add_i32 s50, s73, s15
	v_lshl_add_u64 v[214:215], s[52:53], 0, v[228:229]
	s_mov_b32 m0, s50
	ds_read_b128 v[182:185], v149 offset:16384
	ds_read_b128 v[186:189], v149 offset:17408
	ds_read_b128 v[190:193], v149 offset:18432
	ds_read_b128 v[194:197], v149 offset:19456
	ds_read_b128 v[198:201], v149 offset:20480
	ds_read_b128 v[202:205], v149 offset:21504
	ds_read_b128 v[206:209], v149 offset:22528
	ds_read_b128 v[210:213], v149 offset:23552
	global_load_lds_dwordx4 v[214:215], off
	s_add_i32 m0, s50, 0x2000
	s_add_u32 s50, s52, 0x40000
	v_lshl_add_u64 v[216:217], s[52:53], 0, v[232:233]
	s_addc_u32 s51, s53, 0
	s_add_i32 s78, s74, s15
	global_load_lds_dwordx4 v[216:217], off
	v_lshl_add_u64 v[218:219], s[50:51], 0, v[228:229]
	s_mov_b32 m0, s78
	v_lshl_add_u64 v[220:221], s[54:55], 0, v[230:231]
	global_load_lds_dwordx4 v[218:219], off
	v_lshl_add_u64 v[218:219], s[50:51], 0, v[232:233]
	s_add_i32 m0, s78, 0x2000
	s_nop 0
	global_load_lds_dwordx4 v[218:219], off
	v_lshl_add_u64 v[218:219], s[54:55], 0, v[226:227]
	s_mov_b32 m0, s60
	s_nop 0
	global_load_lds_dwordx4 v[218:219], off
	s_mov_b32 m0, s61
	s_nop 0
	global_load_lds_dwordx4 v[220:221], off
	s_waitcnt vmcnt(8)
	s_waitcnt lgkmcnt(0)
	s_barrier
	v_mfma_f32_16x16x32_bf16 v[90:93], v[150:153], v[182:185], v[90:93]
	v_mfma_f32_16x16x32_bf16 v[90:93], v[154:157], v[186:189], v[90:93]
	v_mfma_f32_16x16x32_bf16 v[26:29], v[162:165], v[186:189], v[26:29]
	v_mfma_f32_16x16x32_bf16 v[26:29], v[158:161], v[182:185], v[26:29]
	v_mfma_f32_16x16x32_bf16 v[114:117], v[166:169], v[182:185], v[114:117]
	v_mfma_f32_16x16x32_bf16 v[114:117], v[170:173], v[186:189], v[114:117]
	v_mfma_f32_16x16x32_bf16 v[50:53], v[178:181], v[186:189], v[50:53]
	v_mfma_f32_16x16x32_bf16 v[50:53], v[174:177], v[182:185], v[50:53]
	v_mfma_f32_16x16x32_bf16 v[54:57], v[174:177], v[190:193], v[54:57]
	v_mfma_f32_16x16x32_bf16 v[54:57], v[178:181], v[194:197], v[54:57]
	v_mfma_f32_16x16x32_bf16 v[118:121], v[170:173], v[194:197], v[118:121]
	v_mfma_f32_16x16x32_bf16 v[118:121], v[166:169], v[190:193], v[118:121]
	v_mfma_f32_16x16x32_bf16 v[38:41], v[158:161], v[190:193], v[38:41]
	v_mfma_f32_16x16x32_bf16 v[38:41], v[162:165], v[194:197], v[38:41]
	v_mfma_f32_16x16x32_bf16 v[102:105], v[154:157], v[194:197], v[102:105]
	v_mfma_f32_16x16x32_bf16 v[102:105], v[150:153], v[190:193], v[102:105]
	v_mfma_f32_16x16x32_bf16 v[106:109], v[150:153], v[198:201], v[106:109]
	v_mfma_f32_16x16x32_bf16 v[106:109], v[154:157], v[202:205], v[106:109]
	v_mfma_f32_16x16x32_bf16 v[42:45], v[162:165], v[202:205], v[42:45]
	v_mfma_f32_16x16x32_bf16 v[42:45], v[158:161], v[198:201], v[42:45]
	v_mfma_f32_16x16x32_bf16 v[122:125], v[166:169], v[198:201], v[122:125]
	v_mfma_f32_16x16x32_bf16 v[122:125], v[170:173], v[202:205], v[122:125]
	v_mfma_f32_16x16x32_bf16 v[58:61], v[178:181], v[202:205], v[58:61]
	v_mfma_f32_16x16x32_bf16 v[58:61], v[174:177], v[198:201], v[58:61]
	v_mfma_f32_16x16x32_bf16 v[62:65], v[174:177], v[206:209], v[62:65]
	v_mfma_f32_16x16x32_bf16 v[62:65], v[178:181], v[210:213], v[62:65]
	v_mfma_f32_16x16x32_bf16 v[126:129], v[170:173], v[210:213], v[126:129]
	v_mfma_f32_16x16x32_bf16 v[126:129], v[166:169], v[206:209], v[126:129]
	v_mfma_f32_16x16x32_bf16 v[46:49], v[158:161], v[206:209], v[46:49]
	v_mfma_f32_16x16x32_bf16 v[46:49], v[162:165], v[210:213], v[46:49]
	v_mfma_f32_16x16x32_bf16 v[110:113], v[154:157], v[210:213], v[110:113]
	v_mfma_f32_16x16x32_bf16 v[110:113], v[150:153], v[206:209], v[110:113]
	s_barrier
	s_add_i32 s78, 0, 0x18000
	s_add_i32 s79, 0, 0x1c000
	v_add_u32_e32 v162, s78, v140
	v_add_u32_e32 v178, s79, v140
	ds_read_b128 v[150:153], v162
	ds_read_b128 v[154:157], v162 offset:1024
	ds_read_b128 v[158:161], v162 offset:2048
	ds_read_b128 v[162:165], v162 offset:3072
	ds_read_b128 v[166:169], v178
	ds_read_b128 v[170:173], v178 offset:1024
	ds_read_b128 v[174:177], v178 offset:2048
	ds_read_b128 v[178:181], v178 offset:3072
	s_add_u32 s50, s54, 0x40000
	s_addc_u32 s51, s55, 0
	s_mov_b32 m0, s62
	v_lshl_add_u64 v[222:223], s[50:51], 0, v[226:227]
	ds_read_b128 v[182:185], v149 offset:32768
	ds_read_b128 v[186:189], v149 offset:33792
	ds_read_b128 v[190:193], v149 offset:34816
	ds_read_b128 v[194:197], v149 offset:35840
	ds_read_b128 v[198:201], v149 offset:36864
	ds_read_b128 v[202:205], v149 offset:37888
	ds_read_b128 v[206:209], v149 offset:38912
	ds_read_b128 v[210:213], v149 offset:39936
	global_load_lds_dwordx4 v[222:223], off
	v_lshl_add_u64 v[222:223], s[50:51], 0, v[230:231]
	s_mov_b32 m0, s63
	s_nop 0
	global_load_lds_dwordx4 v[222:223], off
	s_waitcnt vmcnt(8)
	s_waitcnt lgkmcnt(0)
	s_barrier
	v_mfma_f32_16x16x32_bf16 v[78:81], v[150:153], v[182:185], v[78:81]
	v_mfma_f32_16x16x32_bf16 v[78:81], v[154:157], v[186:189], v[78:81]
	v_mfma_f32_16x16x32_bf16 v[14:17], v[162:165], v[186:189], v[14:17]
	v_mfma_f32_16x16x32_bf16 v[14:17], v[158:161], v[182:185], v[14:17]
	v_mfma_f32_16x16x32_bf16 v[98:101], v[166:169], v[182:185], v[98:101]
	v_mfma_f32_16x16x32_bf16 v[98:101], v[170:173], v[186:189], v[98:101]
	v_mfma_f32_16x16x32_bf16 v[34:37], v[178:181], v[186:189], v[34:37]
	v_mfma_f32_16x16x32_bf16 v[34:37], v[174:177], v[182:185], v[34:37]
	v_mfma_f32_16x16x32_bf16 v[18:21], v[174:177], v[190:193], v[18:21]
	v_mfma_f32_16x16x32_bf16 v[18:21], v[178:181], v[194:197], v[18:21]
	v_mfma_f32_16x16x32_bf16 v[82:85], v[170:173], v[194:197], v[82:85]
	v_mfma_f32_16x16x32_bf16 v[82:85], v[166:169], v[190:193], v[82:85]
	v_mfma_f32_16x16x32_bf16 v[2:5], v[158:161], v[190:193], v[2:5]
	v_mfma_f32_16x16x32_bf16 v[2:5], v[162:165], v[194:197], v[2:5]
	v_mfma_f32_16x16x32_bf16 v[66:69], v[154:157], v[194:197], v[66:69]
	v_mfma_f32_16x16x32_bf16 v[66:69], v[150:153], v[190:193], v[66:69]
	v_mfma_f32_16x16x32_bf16 v[70:73], v[150:153], v[198:201], v[70:73]
	v_mfma_f32_16x16x32_bf16 v[70:73], v[154:157], v[202:205], v[70:73]
	v_mfma_f32_16x16x32_bf16 v[6:9], v[162:165], v[202:205], v[6:9]
	v_mfma_f32_16x16x32_bf16 v[6:9], v[158:161], v[198:201], v[6:9]
	v_mfma_f32_16x16x32_bf16 v[86:89], v[166:169], v[198:201], v[86:89]
	v_mfma_f32_16x16x32_bf16 v[86:89], v[170:173], v[202:205], v[86:89]
	v_mfma_f32_16x16x32_bf16 v[22:25], v[178:181], v[202:205], v[22:25]
	v_mfma_f32_16x16x32_bf16 v[22:25], v[174:177], v[198:201], v[22:25]
	v_mfma_f32_16x16x32_bf16 v[30:33], v[174:177], v[206:209], v[30:33]
	v_mfma_f32_16x16x32_bf16 v[30:33], v[178:181], v[210:213], v[30:33]
	v_mfma_f32_16x16x32_bf16 v[94:97], v[170:173], v[210:213], v[94:97]
	v_mfma_f32_16x16x32_bf16 v[94:97], v[166:169], v[206:209], v[94:97]
	v_mfma_f32_16x16x32_bf16 v[10:13], v[158:161], v[206:209], v[10:13]
	v_mfma_f32_16x16x32_bf16 v[10:13], v[162:165], v[210:213], v[10:13]
	v_mfma_f32_16x16x32_bf16 v[74:77], v[154:157], v[210:213], v[74:77]
	v_mfma_f32_16x16x32_bf16 v[74:77], v[150:153], v[206:209], v[74:77]
	s_barrier
	s_add_i32 s50, s78, s15
	v_lshl_add_u64 v[214:215], v[214:215], 0, s[8:9]
	s_mov_b32 m0, s50
	ds_read_b128 v[182:185], v149 offset:49152
	ds_read_b128 v[186:189], v149 offset:50176
	ds_read_b128 v[190:193], v149 offset:51200
	ds_read_b128 v[194:197], v149 offset:52224
	ds_read_b128 v[198:201], v149 offset:53248
	ds_read_b128 v[202:205], v149 offset:54272
	ds_read_b128 v[206:209], v149 offset:55296
	ds_read_b128 v[210:213], v149 offset:56320
	global_load_lds_dwordx4 v[214:215], off
	s_add_i32 m0, s50, 0x2000
	s_add_u32 s50, s52, 0x40080
	v_lshl_add_u64 v[214:215], v[216:217], 0, s[8:9]
	s_addc_u32 s51, s53, 0
	s_add_i32 s52, s79, s15
	global_load_lds_dwordx4 v[214:215], off
	v_lshl_add_u64 v[214:215], s[50:51], 0, v[228:229]
	s_mov_b32 m0, s52
	s_nop 0
	global_load_lds_dwordx4 v[214:215], off
	v_lshl_add_u64 v[214:215], s[50:51], 0, v[232:233]
	s_add_i32 m0, s52, 0x2000
	s_nop 0
	global_load_lds_dwordx4 v[214:215], off
	v_lshl_add_u64 v[214:215], v[218:219], 0, s[8:9]
	s_mov_b32 m0, s68
	s_nop 0
	global_load_lds_dwordx4 v[214:215], off
	v_lshl_add_u64 v[214:215], v[220:221], 0, s[8:9]
	s_mov_b32 m0, s69
	s_nop 0
	global_load_lds_dwordx4 v[214:215], off
	s_waitcnt vmcnt(8)
	s_waitcnt lgkmcnt(0)
	s_barrier
	v_mfma_f32_16x16x32_bf16 v[90:93], v[150:153], v[182:185], v[90:93]
	v_mfma_f32_16x16x32_bf16 v[90:93], v[154:157], v[186:189], v[90:93]
	v_mfma_f32_16x16x32_bf16 v[26:29], v[162:165], v[186:189], v[26:29]
	v_mfma_f32_16x16x32_bf16 v[26:29], v[158:161], v[182:185], v[26:29]
	v_mfma_f32_16x16x32_bf16 v[114:117], v[166:169], v[182:185], v[114:117]
	v_mfma_f32_16x16x32_bf16 v[114:117], v[170:173], v[186:189], v[114:117]
	v_mfma_f32_16x16x32_bf16 v[50:53], v[178:181], v[186:189], v[50:53]
	v_mfma_f32_16x16x32_bf16 v[50:53], v[174:177], v[182:185], v[50:53]
	v_mfma_f32_16x16x32_bf16 v[54:57], v[174:177], v[190:193], v[54:57]
	v_mfma_f32_16x16x32_bf16 v[54:57], v[178:181], v[194:197], v[54:57]
	v_mfma_f32_16x16x32_bf16 v[118:121], v[170:173], v[194:197], v[118:121]
	v_mfma_f32_16x16x32_bf16 v[118:121], v[166:169], v[190:193], v[118:121]
	v_mfma_f32_16x16x32_bf16 v[38:41], v[158:161], v[190:193], v[38:41]
	v_mfma_f32_16x16x32_bf16 v[38:41], v[162:165], v[194:197], v[38:41]
	v_mfma_f32_16x16x32_bf16 v[102:105], v[154:157], v[194:197], v[102:105]
	v_mfma_f32_16x16x32_bf16 v[102:105], v[150:153], v[190:193], v[102:105]
	v_mfma_f32_16x16x32_bf16 v[106:109], v[150:153], v[198:201], v[106:109]
	v_mfma_f32_16x16x32_bf16 v[106:109], v[154:157], v[202:205], v[106:109]
	v_mfma_f32_16x16x32_bf16 v[42:45], v[162:165], v[202:205], v[42:45]
	v_mfma_f32_16x16x32_bf16 v[42:45], v[158:161], v[198:201], v[42:45]
	v_mfma_f32_16x16x32_bf16 v[122:125], v[166:169], v[198:201], v[122:125]
	v_mfma_f32_16x16x32_bf16 v[122:125], v[170:173], v[202:205], v[122:125]
	v_mfma_f32_16x16x32_bf16 v[58:61], v[178:181], v[202:205], v[58:61]
	v_mfma_f32_16x16x32_bf16 v[58:61], v[174:177], v[198:201], v[58:61]
	v_mfma_f32_16x16x32_bf16 v[62:65], v[174:177], v[206:209], v[62:65]
	v_mfma_f32_16x16x32_bf16 v[62:65], v[178:181], v[210:213], v[62:65]
	v_mfma_f32_16x16x32_bf16 v[126:129], v[170:173], v[210:213], v[126:129]
	v_mfma_f32_16x16x32_bf16 v[126:129], v[166:169], v[206:209], v[126:129]
	v_mfma_f32_16x16x32_bf16 v[46:49], v[158:161], v[206:209], v[46:49]
	v_mfma_f32_16x16x32_bf16 v[46:49], v[162:165], v[210:213], v[46:49]
	v_mfma_f32_16x16x32_bf16 v[110:113], v[154:157], v[210:213], v[110:113]
	v_mfma_f32_16x16x32_bf16 v[110:113], v[150:153], v[206:209], v[110:113]
	s_barrier
	s_add_u32 s34, s34, 0x100
	s_addc_u32 s35, s35, 0
	s_add_u32 s21, s21, 0x100
	s_addc_u32 s23, s23, 0
	s_cmp_ge_i32 s77, s66
	s_mov_b32 s52, s77
	s_cbranch_scc0 .LBB0_872

.LBB0_1009:
	v_add_u32_e32 v0, s64, v187
	ds_read_b128 v[130:133], v0
	ds_read_b128 v[134:137], v0 offset:1024
	ds_read_b128 v[138:141], v0 offset:2048
	ds_read_b128 v[142:145], v0 offset:3072
	v_add_u32_e32 v0, s65, v187
	ds_read_b128 v[146:149], v0
	ds_read_b128 v[150:153], v0 offset:1024
	ds_read_b128 v[178:181], v0 offset:2048
	ds_read_b128 v[182:185], v0 offset:3072
	s_add_i32 s35, s42, 2
	s_add_u32 s43, s36, 0x3fc000
	s_addc_u32 s44, s37, 0
	s_cmp_eq_u32 s61, s42
	s_cselect_b32 s46, s28, s43
	s_cselect_b32 s47, s29, s44
	s_cselect_b32 s44, s30, s11
	s_cselect_b32 s45, s31, s27
	s_add_u32 s42, s46, 0x400000
	s_addc_u32 s43, s47, 0
	v_lshl_add_u64 v[0:1], s[36:37], 0, v[168:169]
	s_add_i32 m0, s51, 0xc000
	ds_read_b128 v[220:223], v215
	ds_read_b128 v[224:227], v215 offset:1024
	ds_read_b128 v[228:231], v215 offset:2048
	ds_read_b128 v[232:235], v215 offset:3072
	ds_read_b128 v[236:239], v215 offset:4096
	ds_read_b128 v[240:243], v215 offset:5120
	ds_read_b128 v[244:247], v215 offset:6144
	ds_read_b128 v[248:251], v215 offset:7168
	global_load_lds_dwordx4 v[0:1], off
	v_lshl_add_u64 v[0:1], s[36:37], 0, v[170:171]
	s_add_i32 m0, s51, 0xe000
	s_nop 0
	global_load_lds_dwordx4 v[0:1], off
	s_waitcnt vmcnt(8)
	s_waitcnt lgkmcnt(0)
	s_barrier
	v_mfma_f32_16x16x32_bf16 v[114:117], v[130:133], v[220:223], v[114:117]
	v_mfma_f32_16x16x32_bf16 v[114:117], v[134:137], v[224:227], v[114:117]
	v_mfma_f32_16x16x32_bf16 v[118:121], v[142:145], v[224:227], v[118:121]
	v_mfma_f32_16x16x32_bf16 v[118:121], v[138:141], v[220:223], v[118:121]
	v_mfma_f32_16x16x32_bf16 v[126:129], v[146:149], v[220:223], v[126:129]
	v_mfma_f32_16x16x32_bf16 v[126:129], v[150:153], v[224:227], v[126:129]
	v_mfma_f32_16x16x32_bf16 v[122:125], v[182:185], v[224:227], v[122:125]
	v_mfma_f32_16x16x32_bf16 v[122:125], v[178:181], v[220:223], v[122:125]
	v_mfma_f32_16x16x32_bf16 v[98:101], v[178:181], v[228:231], v[98:101]
	v_mfma_f32_16x16x32_bf16 v[98:101], v[182:185], v[232:235], v[98:101]
	v_mfma_f32_16x16x32_bf16 v[106:109], v[150:153], v[232:235], v[106:109]
	v_mfma_f32_16x16x32_bf16 v[106:109], v[146:149], v[228:231], v[106:109]
	v_mfma_f32_16x16x32_bf16 v[102:105], v[138:141], v[228:231], v[102:105]
	v_mfma_f32_16x16x32_bf16 v[102:105], v[142:145], v[232:235], v[102:105]
	v_mfma_f32_16x16x32_bf16 v[110:113], v[134:137], v[232:235], v[110:113]
	v_mfma_f32_16x16x32_bf16 v[110:113], v[130:133], v[228:231], v[110:113]
	v_mfma_f32_16x16x32_bf16 v[94:97], v[130:133], v[236:239], v[94:97]
	v_mfma_f32_16x16x32_bf16 v[94:97], v[134:137], v[240:243], v[94:97]
	v_mfma_f32_16x16x32_bf16 v[86:89], v[142:145], v[240:243], v[86:89]
	v_mfma_f32_16x16x32_bf16 v[86:89], v[138:141], v[236:239], v[86:89]
	v_mfma_f32_16x16x32_bf16 v[90:93], v[146:149], v[236:239], v[90:93]
	v_mfma_f32_16x16x32_bf16 v[90:93], v[150:153], v[240:243], v[90:93]
	v_mfma_f32_16x16x32_bf16 v[82:85], v[182:185], v[240:243], v[82:85]
	v_mfma_f32_16x16x32_bf16 v[82:85], v[178:181], v[236:239], v[82:85]
	v_mfma_f32_16x16x32_bf16 v[66:69], v[178:181], v[244:247], v[66:69]
	v_mfma_f32_16x16x32_bf16 v[66:69], v[182:185], v[248:251], v[66:69]
	v_mfma_f32_16x16x32_bf16 v[74:77], v[150:153], v[248:251], v[74:77]
	v_mfma_f32_16x16x32_bf16 v[74:77], v[146:149], v[244:247], v[74:77]
	v_mfma_f32_16x16x32_bf16 v[70:73], v[138:141], v[244:247], v[70:73]
	v_mfma_f32_16x16x32_bf16 v[70:73], v[142:145], v[248:251], v[70:73]
	v_mfma_f32_16x16x32_bf16 v[78:81], v[134:137], v[248:251], v[78:81]
	v_mfma_f32_16x16x32_bf16 v[78:81], v[130:133], v[244:247], v[78:81]
	s_barrier
	s_add_i32 s69, s64, s49
	v_lshl_add_u64 v[252:253], s[44:45], 0, v[156:157]
	s_mov_b32 m0, s69
	ds_read_b128 v[220:223], v215 offset:16384
	ds_read_b128 v[224:227], v215 offset:17408
	ds_read_b128 v[228:231], v215 offset:18432
	ds_read_b128 v[232:235], v215 offset:19456
	ds_read_b128 v[236:239], v215 offset:20480
	ds_read_b128 v[240:243], v215 offset:21504
	ds_read_b128 v[244:247], v215 offset:22528
	ds_read_b128 v[248:251], v215 offset:23552
	global_load_lds_dwordx4 v[252:253], off
	s_add_i32 m0, s69, 0x2000
	s_add_u32 s70, s44, 0xb0000
	v_lshl_add_u64 v[172:173], s[44:45], 0, v[160:161]
	s_addc_u32 s71, s45, 0
	s_add_i32 s69, s65, s49
	global_load_lds_dwordx4 v[172:173], off
	v_lshl_add_u64 v[0:1], s[70:71], 0, v[156:157]
	s_mov_b32 m0, s69
	s_nop 0
	global_load_lds_dwordx4 v[0:1], off
	v_lshl_add_u64 v[0:1], s[70:71], 0, v[160:161]
	s_add_i32 m0, s69, 0x2000
	s_nop 0
	global_load_lds_dwordx4 v[0:1], off
	v_lshl_add_u64 v[0:1], s[46:47], 0, v[154:155]
	s_mov_b32 m0, s51
	s_nop 0
	global_load_lds_dwordx4 v[0:1], off
	v_lshl_add_u64 v[0:1], s[46:47], 0, v[158:159]
	s_mov_b32 m0, s52
	s_nop 0
	global_load_lds_dwordx4 v[0:1], off
	s_waitcnt vmcnt(8)
	s_waitcnt lgkmcnt(0)
	s_barrier
	v_mfma_f32_16x16x32_bf16 v[50:53], v[130:133], v[220:223], v[50:53]
	v_mfma_f32_16x16x32_bf16 v[54:57], v[138:141], v[220:223], v[54:57]
	v_mfma_f32_16x16x32_bf16 v[46:49], v[130:133], v[228:231], v[46:49]
	v_mfma_f32_16x16x32_bf16 v[38:41], v[138:141], v[228:231], v[38:41]
	v_mfma_f32_16x16x32_bf16 v[30:33], v[130:133], v[236:239], v[30:33]
	v_mfma_f32_16x16x32_bf16 v[22:25], v[138:141], v[236:239], v[22:25]
	v_mfma_f32_16x16x32_bf16 v[14:17], v[130:133], v[244:247], v[14:17]
	v_mfma_f32_16x16x32_bf16 v[6:9], v[138:141], v[244:247], v[6:9]
	v_mfma_f32_16x16x32_bf16 v[50:53], v[134:137], v[224:227], v[50:53]
	v_mfma_f32_16x16x32_bf16 v[54:57], v[142:145], v[224:227], v[54:57]
	v_mfma_f32_16x16x32_bf16 v[46:49], v[134:137], v[232:235], v[46:49]
	v_mfma_f32_16x16x32_bf16 v[38:41], v[142:145], v[232:235], v[38:41]
	v_mfma_f32_16x16x32_bf16 v[30:33], v[134:137], v[240:243], v[30:33]
	v_mfma_f32_16x16x32_bf16 v[22:25], v[142:145], v[240:243], v[22:25]
	v_mfma_f32_16x16x32_bf16 v[14:17], v[134:137], v[248:251], v[14:17]
	v_mfma_f32_16x16x32_bf16 v[6:9], v[142:145], v[248:251], v[6:9]
	v_mfma_f32_16x16x32_bf16 v[62:65], v[146:149], v[220:223], v[62:65]
	v_mfma_f32_16x16x32_bf16 v[58:61], v[178:181], v[220:223], v[58:61]
	v_mfma_f32_16x16x32_bf16 v[42:45], v[146:149], v[228:231], v[42:45]
	v_mfma_f32_16x16x32_bf16 v[34:37], v[178:181], v[228:231], v[34:37]
	v_mfma_f32_16x16x32_bf16 v[26:29], v[146:149], v[236:239], v[26:29]
	v_mfma_f32_16x16x32_bf16 v[18:21], v[178:181], v[236:239], v[18:21]
	v_mfma_f32_16x16x32_bf16 v[10:13], v[146:149], v[244:247], v[10:13]
	v_mfma_f32_16x16x32_bf16 v[0:3], v[178:181], v[244:247], v[2:5]
	v_mfma_f32_16x16x32_bf16 v[62:65], v[150:153], v[224:227], v[62:65]
	v_mfma_f32_16x16x32_bf16 v[58:61], v[182:185], v[224:227], v[58:61]
	v_mfma_f32_16x16x32_bf16 v[42:45], v[150:153], v[232:235], v[42:45]
	v_mfma_f32_16x16x32_bf16 v[34:37], v[182:185], v[232:235], v[34:37]
	v_mfma_f32_16x16x32_bf16 v[26:29], v[150:153], v[240:243], v[26:29]
	v_mfma_f32_16x16x32_bf16 v[18:21], v[182:185], v[240:243], v[18:21]
	v_mfma_f32_16x16x32_bf16 v[10:13], v[150:153], v[248:251], v[10:13]
	v_mfma_f32_16x16x32_bf16 v[0:3], v[182:185], v[248:251], v[0:3]
	s_barrier
	s_add_i32 s69, 0, 0x18000
	v_add_u32_e32 v4, s69, v187
	s_add_i32 s70, 0, 0x1c000
	ds_read_b128 v[130:133], v4
	ds_read_b128 v[134:137], v4 offset:1024
	ds_read_b128 v[138:141], v4 offset:2048
	ds_read_b128 v[142:145], v4 offset:3072
	v_add_u32_e32 v4, s70, v187
	ds_read_b128 v[146:149], v4
	ds_read_b128 v[150:153], v4 offset:1024
	ds_read_b128 v[178:181], v4 offset:2048
	ds_read_b128 v[182:185], v4 offset:3072
	s_add_u32 s46, s46, 0x4000
	s_addc_u32 s47, s47, 0
	s_mov_b32 m0, s53
	v_lshl_add_u64 v[4:5], s[46:47], 0, v[154:155]
	ds_read_b128 v[220:223], v215 offset:32768
	ds_read_b128 v[224:227], v215 offset:33792
	ds_read_b128 v[228:231], v215 offset:34816
	ds_read_b128 v[232:235], v215 offset:35840
	ds_read_b128 v[236:239], v215 offset:36864
	ds_read_b128 v[240:243], v215 offset:37888
	ds_read_b128 v[244:247], v215 offset:38912
	ds_read_b128 v[248:251], v215 offset:39936
	global_load_lds_dwordx4 v[4:5], off
	v_lshl_add_u64 v[4:5], s[46:47], 0, v[158:159]
	s_mov_b32 m0, s54
	s_nop 0
	global_load_lds_dwordx4 v[4:5], off
	s_waitcnt vmcnt(8)
	s_waitcnt lgkmcnt(0)
	s_barrier
	v_mfma_f32_16x16x32_bf16 v[114:117], v[130:133], v[220:223], v[114:117]
	v_mfma_f32_16x16x32_bf16 v[114:117], v[134:137], v[224:227], v[114:117]
	v_mfma_f32_16x16x32_bf16 v[118:121], v[142:145], v[224:227], v[118:121]
	v_mfma_f32_16x16x32_bf16 v[118:121], v[138:141], v[220:223], v[118:121]
	v_mfma_f32_16x16x32_bf16 v[126:129], v[146:149], v[220:223], v[126:129]
	v_mfma_f32_16x16x32_bf16 v[126:129], v[150:153], v[224:227], v[126:129]
	v_mfma_f32_16x16x32_bf16 v[122:125], v[182:185], v[224:227], v[122:125]
	v_mfma_f32_16x16x32_bf16 v[122:125], v[178:181], v[220:223], v[122:125]
	v_mfma_f32_16x16x32_bf16 v[98:101], v[178:181], v[228:231], v[98:101]
	v_mfma_f32_16x16x32_bf16 v[98:101], v[182:185], v[232:235], v[98:101]
	v_mfma_f32_16x16x32_bf16 v[106:109], v[150:153], v[232:235], v[106:109]
	v_mfma_f32_16x16x32_bf16 v[106:109], v[146:149], v[228:231], v[106:109]
	v_mfma_f32_16x16x32_bf16 v[102:105], v[138:141], v[228:231], v[102:105]
	v_mfma_f32_16x16x32_bf16 v[102:105], v[142:145], v[232:235], v[102:105]
	v_mfma_f32_16x16x32_bf16 v[110:113], v[134:137], v[232:235], v[110:113]
	v_mfma_f32_16x16x32_bf16 v[110:113], v[130:133], v[228:231], v[110:113]
	v_mfma_f32_16x16x32_bf16 v[94:97], v[130:133], v[236:239], v[94:97]
	v_mfma_f32_16x16x32_bf16 v[94:97], v[134:137], v[240:243], v[94:97]
	v_mfma_f32_16x16x32_bf16 v[86:89], v[142:145], v[240:243], v[86:89]
	v_mfma_f32_16x16x32_bf16 v[86:89], v[138:141], v[236:239], v[86:89]
	v_mfma_f32_16x16x32_bf16 v[90:93], v[146:149], v[236:239], v[90:93]
	v_mfma_f32_16x16x32_bf16 v[90:93], v[150:153], v[240:243], v[90:93]
	v_mfma_f32_16x16x32_bf16 v[82:85], v[182:185], v[240:243], v[82:85]
	v_mfma_f32_16x16x32_bf16 v[82:85], v[178:181], v[236:239], v[82:85]
	v_mfma_f32_16x16x32_bf16 v[66:69], v[178:181], v[244:247], v[66:69]
	v_mfma_f32_16x16x32_bf16 v[66:69], v[182:185], v[248:251], v[66:69]
	v_mfma_f32_16x16x32_bf16 v[74:77], v[150:153], v[248:251], v[74:77]
	v_mfma_f32_16x16x32_bf16 v[74:77], v[146:149], v[244:247], v[74:77]
	v_mfma_f32_16x16x32_bf16 v[70:73], v[138:141], v[244:247], v[70:73]
	v_mfma_f32_16x16x32_bf16 v[70:73], v[142:145], v[248:251], v[70:73]
	v_mfma_f32_16x16x32_bf16 v[78:81], v[134:137], v[248:251], v[78:81]
	v_mfma_f32_16x16x32_bf16 v[78:81], v[130:133], v[244:247], v[78:81]
	s_barrier
	s_add_i32 s46, s69, s49
	v_lshl_add_u64 v[4:5], v[252:253], 0, s[18:19]
	s_mov_b32 m0, s46
	ds_read_b128 v[220:223], v215 offset:49152
	ds_read_b128 v[224:227], v215 offset:50176
	ds_read_b128 v[228:231], v215 offset:51200
	ds_read_b128 v[232:235], v215 offset:52224
	ds_read_b128 v[236:239], v215 offset:53248
	ds_read_b128 v[240:243], v215 offset:54272
	ds_read_b128 v[244:247], v215 offset:55296
	ds_read_b128 v[248:251], v215 offset:56320
	global_load_lds_dwordx4 v[4:5], off
	s_add_i32 m0, s46, 0x2000
	s_add_u32 s44, s44, 0xb0080
	v_lshl_add_u64 v[4:5], v[172:173], 0, s[18:19]
	s_addc_u32 s45, s45, 0
	s_add_i32 s46, s70, s49
	global_load_lds_dwordx4 v[4:5], off
	v_lshl_add_u64 v[4:5], s[44:45], 0, v[156:157]
	s_mov_b32 m0, s46
	s_nop 0
	global_load_lds_dwordx4 v[4:5], off
	v_lshl_add_u64 v[4:5], s[44:45], 0, v[160:161]
	s_add_i32 m0, s46, 0x2000
	s_nop 0
	global_load_lds_dwordx4 v[4:5], off
	v_lshl_add_u64 v[4:5], s[42:43], 0, v[154:155]
	s_mov_b32 m0, s59
	s_nop 0
	global_load_lds_dwordx4 v[4:5], off
	v_lshl_add_u64 v[4:5], s[42:43], 0, v[158:159]
	s_mov_b32 m0, s60
	s_nop 0
	global_load_lds_dwordx4 v[4:5], off
	s_waitcnt vmcnt(8)
	s_waitcnt lgkmcnt(0)
	s_barrier
	v_mfma_f32_16x16x32_bf16 v[50:53], v[130:133], v[220:223], v[50:53]
	v_mfma_f32_16x16x32_bf16 v[54:57], v[138:141], v[220:223], v[54:57]
	v_mfma_f32_16x16x32_bf16 v[46:49], v[130:133], v[228:231], v[46:49]
	v_mfma_f32_16x16x32_bf16 v[38:41], v[138:141], v[228:231], v[38:41]
	v_mfma_f32_16x16x32_bf16 v[30:33], v[130:133], v[236:239], v[30:33]
	v_mfma_f32_16x16x32_bf16 v[22:25], v[138:141], v[236:239], v[22:25]
	v_mfma_f32_16x16x32_bf16 v[14:17], v[130:133], v[244:247], v[14:17]
	v_mfma_f32_16x16x32_bf16 v[4:7], v[138:141], v[244:247], v[6:9]
	v_mfma_f32_16x16x32_bf16 v[50:53], v[134:137], v[224:227], v[50:53]
	v_mfma_f32_16x16x32_bf16 v[54:57], v[142:145], v[224:227], v[54:57]
	v_mfma_f32_16x16x32_bf16 v[46:49], v[134:137], v[232:235], v[46:49]
	v_mfma_f32_16x16x32_bf16 v[38:41], v[142:145], v[232:235], v[38:41]
	v_mfma_f32_16x16x32_bf16 v[30:33], v[134:137], v[240:243], v[30:33]
	v_mfma_f32_16x16x32_bf16 v[22:25], v[142:145], v[240:243], v[22:25]
	v_mfma_f32_16x16x32_bf16 v[14:17], v[134:137], v[248:251], v[14:17]
	v_mfma_f32_16x16x32_bf16 v[6:9], v[142:145], v[248:251], v[4:7]
	v_mfma_f32_16x16x32_bf16 v[62:65], v[146:149], v[220:223], v[62:65]
	v_mfma_f32_16x16x32_bf16 v[58:61], v[178:181], v[220:223], v[58:61]
	v_mfma_f32_16x16x32_bf16 v[42:45], v[146:149], v[228:231], v[42:45]
	v_mfma_f32_16x16x32_bf16 v[34:37], v[178:181], v[228:231], v[34:37]
	v_mfma_f32_16x16x32_bf16 v[26:29], v[146:149], v[236:239], v[26:29]
	v_mfma_f32_16x16x32_bf16 v[18:21], v[178:181], v[236:239], v[18:21]
	v_mfma_f32_16x16x32_bf16 v[10:13], v[146:149], v[244:247], v[10:13]
	v_mfma_f32_16x16x32_bf16 v[0:3], v[178:181], v[244:247], v[0:3]
	v_mfma_f32_16x16x32_bf16 v[62:65], v[150:153], v[224:227], v[62:65]
	v_mfma_f32_16x16x32_bf16 v[58:61], v[182:185], v[224:227], v[58:61]
	v_mfma_f32_16x16x32_bf16 v[42:45], v[150:153], v[232:235], v[42:45]
	v_mfma_f32_16x16x32_bf16 v[34:37], v[182:185], v[232:235], v[34:37]
	v_mfma_f32_16x16x32_bf16 v[26:29], v[150:153], v[240:243], v[26:29]
	v_mfma_f32_16x16x32_bf16 v[18:21], v[182:185], v[240:243], v[18:21]
	v_mfma_f32_16x16x32_bf16 v[10:13], v[150:153], v[248:251], v[10:13]
	v_mfma_f32_16x16x32_bf16 v[2:5], v[182:185], v[248:251], v[0:3]
	s_barrier
	s_add_u32 s11, s11, 0x100
	s_addc_u32 s27, s27, 0
	s_add_u32 s36, s36, 0x800000
	s_addc_u32 s37, s37, 0
	s_cmp_ge_i32 s35, s58
	s_mov_b32 s42, s35
	s_cbranch_scc0 .LBB0_1009
	v_mov_b64_e32 v[234:235], v[174:175]
	s_and_b64 vcc, exec, s[22:23]
	s_cbranch_vccnz .LBB0_980
	s_branch .LBB0_981
